# streaming cache policy: nt on all P0 global loads (f32 weights / GEMV, single use) on top of the P13 nt stores
# baseline (speedup 1.0000x reference)
; __device__ __forceinline__ float siluf_(float x) { return x * sigmoidf_(x); }
; __device__ __forceinline__ void p0_phase(const Args& a, LAS unsigned char* lds) {
;     ...
;         for (int i = tid; i < 3 * D; i += NTHREADS) { const int j = i / D, k = i % D; const float v = j < 2 ? a.in[I_C][j * D + k] : a.in[I_CCTX][k]; sc[i] = siluf_(v); }
.LBB0_8:
	s_or_b64 exec, exec, s[6:7]
	global_load_dword v2, v[4:5], off nt
	v_add_u32_e32 v5, 0x200, v6
	v_cmp_lt_i32_e32 vcc, s9, v6
	s_or_b64 s[4:5], vcc, s[4:5]
	v_mov_b32_e32 v6, v5
	s_waitcnt vmcnt(0)
	v_mul_f32_e32 v4, 0xbfb8aa3b, v2
	v_exp_f32_e32 v4, v4
	s_nop 0
	v_add_f32_e32 v4, 1.0, v4
	v_rcp_f32_e32 v4, v4
	s_nop 0
	v_mul_f32_e32 v2, v2, v4
	ds_write_b32 v1, v2
	v_add_u32_e32 v1, 0x800, v1
	s_andn2_b64 exec, exec, s[4:5]
	s_cbranch_execz .LBB0_13

; #define GAS __attribute__((address_space(1)))
; __device__ __forceinline__ void p0_phase(const Args& a, LAS unsigned char* lds) {
;     ...
;             if (tid < 384) {
;                 const int cg = tid % 24, ks = tid / 24;
;                 f32x4 a0 = {0.f, 0.f, 0.f, 0.f}, a1 = a0, a2 = a0;
;                 const float* wp = W + (size_t)(ks * 256) * (3 * D) + cb + 4 * cg;
; #pragma unroll 32
;                 for (int r = 0; r < 256; ++r) {
;                     const f32x4 w = *(const GAS f32x4*)(wp + (size_t)r * (3 * D));
;                     const int k = ks * 256 + r;
;                     a0 += w * sc[k]; a1 += w * sc[D + k]; a2 += w * sc[2 * D + k];
;                 }
.LBB0_18:
	v_lshl_add_u64 v[50:51], v[60:61], 0, s[16:17]
	ds_read_b128 v[62:65], v80
	ds_read_b128 v[18:21], v80 offset:16
	ds_read_b128 v[22:25], v80 offset:32
	ds_read_b128 v[2:5], v80 offset:48
	ds_read_b128 v[14:17], v80 offset:16384
	ds_read_b128 v[26:29], v80 offset:16400
	ds_read_b128 v[38:41], v80 offset:32768
	ds_read_b128 v[46:49], v80 offset:32784
	ds_read_b128 v[6:9], v80 offset:16416
	ds_read_b128 v[10:13], v80 offset:32800
	global_load_dwordx4 v[66:69], v[50:51], off nt
	v_add_co_u32_e64 v52, s[0:1], s11, v50
	s_add_u32 s16, s16, 0x180000
	s_nop 0
	v_addc_co_u32_e64 v53, s[0:1], 0, v51, s[0:1]
	global_load_dwordx4 v[70:73], v[52:53], off nt
	s_mov_b32 s0, 0x18000
	s_addc_u32 s17, s17, 0
	s_cmp_eq_u32 s16, 0xc00000
	s_waitcnt vmcnt(1) lgkmcnt(9)
	v_pk_fma_f32 v[74:75], v[66:67], v[62:63], v[30:31] op_sel_hi:[1,0,1]
	v_add_co_u32_e64 v30, s[0:1], s0, v50
	s_waitcnt lgkmcnt(5)
	v_pk_fma_f32 v[34:35], v[66:67], v[14:15], v[34:35] op_sel_hi:[1,0,1]
	v_addc_co_u32_e64 v31, s[0:1], 0, v51, s[0:1]
	s_mov_b32 s0, 0x24000
	s_waitcnt lgkmcnt(3)
	v_pk_fma_f32 v[42:43], v[66:67], v[38:39], v[42:43] op_sel_hi:[1,0,1]
	v_add_co_u32_e64 v66, s[0:1], s0, v50
	v_pk_fma_f32 v[52:53], v[68:69], v[62:63], v[32:33] op_sel_hi:[1,0,1]
	v_pk_fma_f32 v[44:45], v[68:69], v[38:39], v[44:45] op_sel_hi:[1,0,1]
	v_addc_co_u32_e64 v67, s[0:1], 0, v51, s[0:1]
	global_load_dwordx4 v[30:33], v[30:31], off nt
	v_pk_fma_f32 v[36:37], v[68:69], v[14:15], v[36:37] op_sel_hi:[1,0,1]
	s_waitcnt vmcnt(1)
	v_pk_fma_f32 v[68:69], v[70:71], v[62:63], v[74:75] op_sel:[0,1,0]
	v_pk_fma_f32 v[52:53], v[72:73], v[62:63], v[52:53] op_sel:[0,1,0]
	v_pk_fma_f32 v[34:35], v[70:71], v[14:15], v[34:35] op_sel:[0,1,0]
	v_pk_fma_f32 v[62:63], v[70:71], v[38:39], v[42:43] op_sel:[0,1,0]
	v_pk_fma_f32 v[70:71], v[72:73], v[38:39], v[44:45] op_sel:[0,1,0]
	global_load_dwordx4 v[42:45], v[66:67], off nt
	v_mov_b32_e32 v66, v65
	s_mov_b32 s0, 0x30000
	v_pk_fma_f32 v[14:15], v[72:73], v[14:15], v[36:37] op_sel:[0,1,0]
	ds_read_b128 v[36:39], v80 offset:16432
	s_waitcnt vmcnt(1)
	v_pk_fma_f32 v[52:53], v[32:33], v[64:65], v[52:53] op_sel_hi:[1,0,1]
	v_pk_fma_f32 v[64:65], v[30:31], v[64:65], v[68:69] op_sel_hi:[1,0,1]
	v_pk_fma_f32 v[68:69], v[32:33], v[16:17], v[14:15] op_sel_hi:[1,0,1]
	v_pk_fma_f32 v[72:73], v[30:31], v[16:17], v[34:35] op_sel_hi:[1,0,1]
	v_pk_fma_f32 v[70:71], v[32:33], v[40:41], v[70:71] op_sel_hi:[1,0,1]
	v_pk_fma_f32 v[30:31], v[30:31], v[40:41], v[62:63] op_sel_hi:[1,0,1]
	v_mov_b32_e32 v40, v17
	s_waitcnt vmcnt(0)
	v_pk_fma_f32 v[52:53], v[44:45], v[66:67], v[52:53] op_sel_hi:[1,0,1]
	v_pk_fma_f32 v[66:67], v[42:43], v[66:67], v[64:65] op_sel_hi:[1,0,1]
	v_add_co_u32_e64 v64, s[0:1], s0, v50
	v_mov_b32_e32 v62, v41
	s_nop 0
	v_addc_co_u32_e64 v65, s[0:1], 0, v51, s[0:1]
	s_mov_b32 s0, 0x3c000
	s_nop 0
	v_add_co_u32_e64 v74, s[0:1], s0, v50
	ds_read_b128 v[32:35], v80 offset:32816
	ds_read_b128 v[14:17], v80 offset:64
	v_pk_fma_f32 v[68:69], v[44:45], v[40:41], v[68:69] op_sel_hi:[1,0,1]
	v_pk_fma_f32 v[72:73], v[42:43], v[40:41], v[72:73] op_sel_hi:[1,0,1]
	v_addc_co_u32_e64 v75, s[0:1], 0, v51, s[0:1]
	v_pk_fma_f32 v[44:45], v[44:45], v[62:63], v[70:71] op_sel_hi:[1,0,1]
	v_pk_fma_f32 v[30:31], v[42:43], v[62:63], v[30:31] op_sel_hi:[1,0,1]
	global_load_dwordx4 v[40:43], v[64:65], off nt
	s_nop 0
	global_load_dwordx4 v[62:65], v[74:75], off nt
	s_mov_b32 s0, 0x48000
	v_add_co_u32_e64 v70, s[0:1], s0, v50
	s_waitcnt vmcnt(1)
	v_pk_fma_f32 v[52:53], v[42:43], v[18:19], v[52:53] op_sel_hi:[1,0,1]
	v_addc_co_u32_e64 v71, s[0:1], 0, v51, s[0:1]
	s_mov_b32 s0, 0x54000
	s_nop 0
	v_add_co_u32_e64 v74, s[0:1], s0, v50
	v_pk_fma_f32 v[66:67], v[40:41], v[18:19], v[66:67] op_sel_hi:[1,0,1]
	v_pk_fma_f32 v[68:69], v[42:43], v[26:27], v[68:69] op_sel_hi:[1,0,1]
	v_pk_fma_f32 v[72:73], v[40:41], v[26:27], v[72:73] op_sel_hi:[1,0,1]
	s_waitcnt lgkmcnt(5)
	v_pk_fma_f32 v[44:45], v[42:43], v[46:47], v[44:45] op_sel_hi:[1,0,1]
	v_pk_fma_f32 v[30:31], v[40:41], v[46:47], v[30:31] op_sel_hi:[1,0,1]
	v_addc_co_u32_e64 v75, s[0:1], 0, v51, s[0:1]
	global_load_dwordx4 v[40:43], v[70:71], off nt
	s_waitcnt vmcnt(1)
	v_pk_fma_f32 v[52:53], v[64:65], v[18:19], v[52:53] op_sel:[0,1,0]
	v_pk_fma_f32 v[18:19], v[62:63], v[18:19], v[66:67] op_sel:[0,1,0]
	v_pk_fma_f32 v[66:67], v[64:65], v[26:27], v[68:69] op_sel:[0,1,0]
	v_pk_fma_f32 v[26:27], v[62:63], v[26:27], v[72:73] op_sel:[0,1,0]
	v_pk_fma_f32 v[68:69], v[64:65], v[46:47], v[44:45] op_sel:[0,1,0]
	v_pk_fma_f32 v[30:31], v[62:63], v[46:47], v[30:31] op_sel:[0,1,0]
	global_load_dwordx4 v[62:65], v[74:75], off nt
	v_mov_b32_e32 v70, v21
	s_mov_b32 s0, 0x60000
	ds_read_b128 v[44:47], v80 offset:16448
	s_waitcnt vmcnt(1)
	v_pk_fma_f32 v[52:53], v[42:43], v[20:21], v[52:53] op_sel_hi:[1,0,1]
	v_pk_fma_f32 v[72:73], v[40:41], v[20:21], v[18:19] op_sel_hi:[1,0,1]
	v_pk_fma_f32 v[66:67], v[42:43], v[28:29], v[66:67] op_sel_hi:[1,0,1]
	v_pk_fma_f32 v[26:27], v[40:41], v[28:29], v[26:27] op_sel_hi:[1,0,1]
	v_pk_fma_f32 v[68:69], v[42:43], v[48:49], v[68:69] op_sel_hi:[1,0,1]
	v_pk_fma_f32 v[30:31], v[40:41], v[48:49], v[30:31] op_sel_hi:[1,0,1]
	v_mov_b32_e32 v28, v29
	s_waitcnt vmcnt(0)
; #define GAS __attribute__((address_space(1)))
; __device__ __forceinline__ void p0_phase(const Args& a, LAS unsigned char* lds) {
;     ...
;                 for (int r = 0; r < 256; ++r) {
;                     const f32x4 w = *(const GAS f32x4*)(wp + (size_t)r * (3 * D));
;                     const int k = ks * 256 + r;
;                     a0 += w * sc[k]; a1 += w * sc[D + k]; a2 += w * sc[2 * D + k];
;                 }
	v_pk_fma_f32 v[52:53], v[64:65], v[70:71], v[52:53] op_sel_hi:[1,0,1]
	v_pk_fma_f32 v[70:71], v[62:63], v[70:71], v[72:73] op_sel_hi:[1,0,1]
	v_add_co_u32_e64 v72, s[0:1], s0, v50
	v_mov_b32_e32 v48, v49
	s_nop 0
	v_addc_co_u32_e64 v73, s[0:1], 0, v51, s[0:1]
	s_mov_b32 s0, 0x6c000
	s_nop 0
	v_add_co_u32_e64 v76, s[0:1], s0, v50
	ds_read_b128 v[40:43], v80 offset:32832
	ds_read_b128 v[18:21], v80 offset:80
	v_pk_fma_f32 v[66:67], v[64:65], v[28:29], v[66:67] op_sel_hi:[1,0,1]
	v_pk_fma_f32 v[74:75], v[62:63], v[28:29], v[26:27] op_sel_hi:[1,0,1]
	v_addc_co_u32_e64 v77, s[0:1], 0, v51, s[0:1]
	v_pk_fma_f32 v[68:69], v[64:65], v[48:49], v[68:69] op_sel_hi:[1,0,1]
	v_pk_fma_f32 v[30:31], v[62:63], v[48:49], v[30:31] op_sel_hi:[1,0,1]
	global_load_dwordx4 v[26:29], v[72:73], off nt
	global_load_dwordx4 v[62:65], v[76:77], off nt
	s_mov_b32 s0, 0x78000
	v_add_co_u32_e64 v48, s[0:1], s0, v50
	s_waitcnt vmcnt(1)
	v_pk_fma_f32 v[52:53], v[28:29], v[22:23], v[52:53] op_sel_hi:[1,0,1]
	v_addc_co_u32_e64 v49, s[0:1], 0, v51, s[0:1]
	s_waitcnt lgkmcnt(7)
	v_pk_fma_f32 v[72:73], v[28:29], v[6:7], v[66:67] op_sel_hi:[1,0,1]
	s_waitcnt lgkmcnt(6)
	v_pk_fma_f32 v[28:29], v[28:29], v[10:11], v[68:69] op_sel_hi:[1,0,1]
	s_mov_b32 s0, 0x84000
	global_load_dwordx4 v[66:69], v[48:49], off nt
	v_pk_fma_f32 v[70:71], v[26:27], v[22:23], v[70:71] op_sel_hi:[1,0,1]
	v_pk_fma_f32 v[74:75], v[26:27], v[6:7], v[74:75] op_sel_hi:[1,0,1]
	v_pk_fma_f32 v[26:27], v[26:27], v[10:11], v[30:31] op_sel_hi:[1,0,1]
	v_add_co_u32_e64 v30, s[0:1], s0, v50
	s_waitcnt vmcnt(1)
	v_pk_fma_f32 v[48:49], v[64:65], v[22:23], v[52:53] op_sel:[0,1,0]
	v_addc_co_u32_e64 v31, s[0:1], 0, v51, s[0:1]
	v_pk_fma_f32 v[22:23], v[62:63], v[22:23], v[70:71] op_sel:[0,1,0]
	v_pk_fma_f32 v[52:53], v[64:65], v[6:7], v[72:73] op_sel:[0,1,0]
	v_pk_fma_f32 v[6:7], v[62:63], v[6:7], v[74:75] op_sel:[0,1,0]
	v_pk_fma_f32 v[70:71], v[64:65], v[10:11], v[28:29] op_sel:[0,1,0]
	v_pk_fma_f32 v[10:11], v[62:63], v[10:11], v[26:27] op_sel:[0,1,0]
	global_load_dwordx4 v[62:65], v[30:31], off nt
	s_mov_b32 s0, 0x90000
	v_mov_b32_e32 v72, v25
	ds_read_b128 v[28:31], v80 offset:16464
	s_waitcnt vmcnt(1)
	v_pk_fma_f32 v[48:49], v[68:69], v[24:25], v[48:49] op_sel_hi:[1,0,1]
	v_pk_fma_f32 v[52:53], v[68:69], v[8:9], v[52:53] op_sel_hi:[1,0,1]
	v_pk_fma_f32 v[68:69], v[68:69], v[12:13], v[70:71] op_sel_hi:[1,0,1]
	v_add_co_u32_e64 v70, s[0:1], s0, v50
	v_pk_fma_f32 v[22:23], v[66:67], v[24:25], v[22:23] op_sel_hi:[1,0,1]
	s_nop 0
	v_addc_co_u32_e64 v71, s[0:1], 0, v51, s[0:1]
	v_pk_fma_f32 v[74:75], v[66:67], v[8:9], v[6:7] op_sel_hi:[1,0,1]
	v_pk_fma_f32 v[10:11], v[66:67], v[12:13], v[10:11] op_sel_hi:[1,0,1]
	v_mov_b32_e32 v12, v9
	s_mov_b32 s0, 0x9c000
	v_mov_b32_e32 v66, v13
	ds_read_b128 v[24:27], v80 offset:32848
	ds_read_b128 v[6:9], v80 offset:96
	s_waitcnt vmcnt(0)
	v_pk_fma_f32 v[48:49], v[64:65], v[72:73], v[48:49] op_sel_hi:[1,0,1]
	v_pk_fma_f32 v[22:23], v[62:63], v[72:73], v[22:23] op_sel_hi:[1,0,1]
	v_pk_fma_f32 v[72:73], v[62:63], v[12:13], v[74:75] op_sel_hi:[1,0,1]
	v_add_co_u32_e64 v74, s[0:1], s0, v50
	v_pk_fma_f32 v[52:53], v[64:65], v[12:13], v[52:53] op_sel_hi:[1,0,1]
	s_nop 0
	v_addc_co_u32_e64 v75, s[0:1], 0, v51, s[0:1]
	v_pk_fma_f32 v[68:69], v[64:65], v[66:67], v[68:69] op_sel_hi:[1,0,1]
	v_pk_fma_f32 v[66:67], v[62:63], v[66:67], v[10:11] op_sel_hi:[1,0,1]
	global_load_dwordx4 v[10:13], v[70:71], off nt
	global_load_dwordx4 v[62:65], v[74:75], off nt
	s_mov_b32 s0, 0xa8000
	v_add_co_u32_e64 v76, s[0:1], s0, v50
	s_waitcnt vmcnt(1)
	v_pk_fma_f32 v[48:49], v[12:13], v[2:3], v[48:49] op_sel_hi:[1,0,1]
	v_addc_co_u32_e64 v77, s[0:1], 0, v51, s[0:1]
	v_pk_fma_f32 v[22:23], v[10:11], v[2:3], v[22:23] op_sel_hi:[1,0,1]
	s_waitcnt lgkmcnt(8)
	v_pk_fma_f32 v[52:53], v[12:13], v[36:37], v[52:53] op_sel_hi:[1,0,1]
	v_pk_fma_f32 v[70:71], v[10:11], v[36:37], v[72:73] op_sel_hi:[1,0,1]
	s_waitcnt lgkmcnt(7)
	v_pk_fma_f32 v[12:13], v[12:13], v[32:33], v[68:69] op_sel_hi:[1,0,1]
	v_pk_fma_f32 v[10:11], v[10:11], v[32:33], v[66:67] op_sel_hi:[1,0,1]
	global_load_dwordx4 v[66:69], v[76:77], off nt
	s_mov_b32 s0, 0xb4000
	v_add_co_u32_e64 v72, s[0:1], s0, v50
	s_waitcnt vmcnt(1)
	v_pk_fma_f32 v[48:49], v[64:65], v[2:3], v[48:49] op_sel:[0,1,0]
	v_addc_co_u32_e64 v73, s[0:1], 0, v51, s[0:1]
	v_pk_fma_f32 v[2:3], v[62:63], v[2:3], v[22:23] op_sel:[0,1,0]
	v_pk_fma_f32 v[22:23], v[64:65], v[36:37], v[52:53] op_sel:[0,1,0]
	v_pk_fma_f32 v[36:37], v[62:63], v[36:37], v[70:71] op_sel:[0,1,0]
	v_pk_fma_f32 v[52:53], v[64:65], v[32:33], v[12:13] op_sel:[0,1,0]
	v_pk_fma_f32 v[32:33], v[62:63], v[32:33], v[10:11] op_sel:[0,1,0]
	global_load_dwordx4 v[62:65], v[72:73], off nt
	s_mov_b32 s0, 0xc0000
	v_mov_b32_e32 v70, v5
	ds_read_b128 v[10:13], v80 offset:16480
	s_waitcnt vmcnt(1)
	v_pk_fma_f32 v[22:23], v[68:69], v[38:39], v[22:23] op_sel_hi:[1,0,1]
	v_pk_fma_f32 v[36:37], v[66:67], v[38:39], v[36:37] op_sel_hi:[1,0,1]
	v_add_co_u32_e64 v38, s[0:1], s0, v50
	v_pk_fma_f32 v[52:53], v[68:69], v[34:35], v[52:53] op_sel_hi:[1,0,1]
	v_pk_fma_f32 v[32:33], v[66:67], v[34:35], v[32:33] op_sel_hi:[1,0,1]
	v_mov_b32_e32 v34, v39
	v_addc_co_u32_e64 v39, s[0:1], 0, v51, s[0:1]
	s_mov_b32 s0, 0xcc000
	v_pk_fma_f32 v[48:49], v[68:69], v[4:5], v[48:49] op_sel_hi:[1,0,1]
	v_pk_fma_f32 v[72:73], v[66:67], v[4:5], v[2:3] op_sel_hi:[1,0,1]
	v_mov_b32_e32 v66, v35
	v_add_co_u32_e64 v68, s[0:1], s0, v50
	ds_read_b128 v[2:5], v80 offset:32864
	s_nop 0
	v_addc_co_u32_e64 v69, s[0:1], 0, v51, s[0:1]
	s_waitcnt vmcnt(0)
; #define GAS __attribute__((address_space(1)))
; __device__ __forceinline__ void p0_phase(const Args& a, LAS unsigned char* lds) {
;     ...
;                 for (int r = 0; r < 256; ++r) {
;                     const f32x4 w = *(const GAS f32x4*)(wp + (size_t)r * (3 * D));
;                     const int k = ks * 256 + r;
;                     a0 += w * sc[k]; a1 += w * sc[D + k]; a2 += w * sc[2 * D + k];
;                 }
	v_pk_fma_f32 v[48:49], v[64:65], v[70:71], v[48:49] op_sel_hi:[1,0,1]
	v_pk_fma_f32 v[70:71], v[62:63], v[70:71], v[72:73] op_sel_hi:[1,0,1]
	v_pk_fma_f32 v[22:23], v[64:65], v[34:35], v[22:23] op_sel_hi:[1,0,1]
	v_pk_fma_f32 v[74:75], v[62:63], v[34:35], v[36:37] op_sel_hi:[1,0,1]
	v_pk_fma_f32 v[62:63], v[62:63], v[66:67], v[32:33] op_sel_hi:[1,0,1]
	global_load_dwordx4 v[32:35], v[38:39], off nt
	s_nop 0
	global_load_dwordx4 v[36:39], v[68:69], off nt
	s_mov_b32 s0, 0xd8000
	v_add_co_u32_e64 v72, s[0:1], s0, v50
	v_pk_fma_f32 v[52:53], v[64:65], v[66:67], v[52:53] op_sel_hi:[1,0,1]
	s_nop 0
	v_addc_co_u32_e64 v73, s[0:1], 0, v51, s[0:1]
	s_mov_b32 s0, 0xe4000
	s_nop 0
	v_add_co_u32_e64 v76, s[0:1], s0, v50
	s_waitcnt vmcnt(1) lgkmcnt(8)
	v_pk_fma_f32 v[48:49], v[34:35], v[14:15], v[48:49] op_sel_hi:[1,0,1]
	v_pk_fma_f32 v[64:65], v[32:33], v[14:15], v[70:71] op_sel_hi:[1,0,1]
	s_waitcnt lgkmcnt(7)
	v_pk_fma_f32 v[66:67], v[34:35], v[44:45], v[22:23] op_sel_hi:[1,0,1]
	v_pk_fma_f32 v[68:69], v[32:33], v[44:45], v[74:75] op_sel_hi:[1,0,1]
	s_waitcnt lgkmcnt(6)
	v_pk_fma_f32 v[34:35], v[34:35], v[40:41], v[52:53] op_sel_hi:[1,0,1]
	v_pk_fma_f32 v[32:33], v[32:33], v[40:41], v[62:63] op_sel_hi:[1,0,1]
	v_addc_co_u32_e64 v77, s[0:1], 0, v51, s[0:1]
	s_waitcnt vmcnt(0)
	v_pk_fma_f32 v[48:49], v[38:39], v[14:15], v[48:49] op_sel:[0,1,0]
	v_pk_fma_f32 v[14:15], v[36:37], v[14:15], v[64:65] op_sel:[0,1,0]
	v_pk_fma_f32 v[62:63], v[38:39], v[44:45], v[66:67] op_sel:[0,1,0]
	v_pk_fma_f32 v[44:45], v[36:37], v[44:45], v[68:69] op_sel:[0,1,0]
	v_pk_fma_f32 v[38:39], v[38:39], v[40:41], v[34:35] op_sel:[0,1,0]
	v_pk_fma_f32 v[36:37], v[36:37], v[40:41], v[32:33] op_sel:[0,1,0]
	global_load_dwordx4 v[32:35], v[72:73], off nt
	global_load_dwordx4 v[64:67], v[76:77], off nt
	s_mov_b32 s0, 0xf0000
	v_add_co_u32_e64 v82, s[0:1], s0, v50
	v_mov_b32_e32 v72, v43
	s_nop 0
	v_addc_co_u32_e64 v83, s[0:1], 0, v51, s[0:1]
	s_mov_b32 s0, 0xfc000
	s_nop 0
	v_add_co_u32_e64 v52, s[0:1], s0, v50
	s_waitcnt vmcnt(1)
	v_pk_fma_f32 v[48:49], v[34:35], v[16:17], v[48:49] op_sel_hi:[1,0,1]
	v_pk_fma_f32 v[14:15], v[32:33], v[16:17], v[14:15] op_sel_hi:[1,0,1]
	v_pk_fma_f32 v[68:69], v[34:35], v[46:47], v[62:63] op_sel_hi:[1,0,1]
	v_pk_fma_f32 v[70:71], v[32:33], v[46:47], v[44:45] op_sel_hi:[1,0,1]
	v_pk_fma_f32 v[34:35], v[34:35], v[42:43], v[38:39] op_sel_hi:[1,0,1]
	v_pk_fma_f32 v[32:33], v[32:33], v[42:43], v[36:37] op_sel_hi:[1,0,1]
	v_mov_b32_e32 v16, v17
	v_addc_co_u32_e64 v53, s[0:1], 0, v51, s[0:1]
	s_waitcnt vmcnt(0)
	v_pk_fma_f32 v[48:49], v[66:67], v[16:17], v[48:49] op_sel_hi:[1,0,1]
	v_pk_fma_f32 v[74:75], v[64:65], v[16:17], v[14:15] op_sel_hi:[1,0,1]
	v_pk_fma_f32 v[84:85], v[66:67], v[72:73], v[34:35] op_sel_hi:[1,0,1]
	v_pk_fma_f32 v[72:73], v[64:65], v[72:73], v[32:33] op_sel_hi:[1,0,1]
	global_load_dwordx4 v[14:17], v[82:83], off nt
	global_load_dwordx4 v[32:35], v[52:53], off nt
	s_mov_b32 s0, 0x108000
	v_add_co_u32_e64 v22, s[0:1], s0, v50
	v_mov_b32_e32 v46, v47
	s_nop 0
	v_addc_co_u32_e64 v23, s[0:1], 0, v51, s[0:1]
	s_mov_b32 s0, 0x114000
	s_nop 0
	v_add_co_u32_e64 v44, s[0:1], s0, v50
	v_pk_fma_f32 v[76:77], v[66:67], v[46:47], v[68:69] op_sel_hi:[1,0,1]
	s_nop 0
	v_addc_co_u32_e64 v45, s[0:1], 0, v51, s[0:1]
	s_mov_b32 s0, 0x120000
	s_nop 0
	v_add_co_u32_e64 v36, s[0:1], s0, v50
	v_pk_fma_f32 v[70:71], v[64:65], v[46:47], v[70:71] op_sel_hi:[1,0,1]
	s_nop 0
	v_addc_co_u32_e64 v37, s[0:1], 0, v51, s[0:1]
	s_mov_b32 s0, 0x12c000
	s_nop 0
	v_add_co_u32_e64 v38, s[0:1], s0, v50
	s_waitcnt lgkmcnt(3)
	v_mov_b32_e32 v82, v27
	v_addc_co_u32_e64 v39, s[0:1], 0, v51, s[0:1]
	s_mov_b32 s0, 0x138000
	s_nop 0
	v_add_co_u32_e64 v40, s[0:1], s0, v50
	s_waitcnt vmcnt(1)
	v_pk_fma_f32 v[46:47], v[16:17], v[18:19], v[48:49] op_sel_hi:[1,0,1]
	v_addc_co_u32_e64 v41, s[0:1], 0, v51, s[0:1]
	v_add_co_u32_e64 v42, s[0:1], s14, v50
	v_pk_fma_f32 v[48:49], v[14:15], v[18:19], v[74:75] op_sel_hi:[1,0,1]
	s_nop 0
	v_addc_co_u32_e64 v43, s[0:1], 0, v51, s[0:1]
	v_add_co_u32_e64 v62, s[0:1], s15, v50
	v_pk_fma_f32 v[52:53], v[14:15], v[28:29], v[70:71] op_sel_hi:[1,0,1]
	s_nop 0
	v_addc_co_u32_e64 v63, s[0:1], 0, v51, s[0:1]
	v_add_co_u32_e64 v68, s[0:1], s18, v50
	v_pk_fma_f32 v[70:71], v[16:17], v[24:25], v[84:85] op_sel_hi:[1,0,1]
	s_nop 0
	v_addc_co_u32_e64 v69, s[0:1], 0, v51, s[0:1]
	v_add_co_u32_e64 v64, s[0:1], s19, v50
	v_pk_fma_f32 v[72:73], v[14:15], v[24:25], v[72:73] op_sel_hi:[1,0,1]
	s_nop 0
	v_addc_co_u32_e64 v65, s[0:1], 0, v51, s[0:1]
	v_add_co_u32_e64 v66, s[0:1], s20, v50
	s_waitcnt vmcnt(0)
	v_pk_fma_f32 v[46:47], v[34:35], v[18:19], v[46:47] op_sel:[0,1,0]
	v_addc_co_u32_e64 v67, s[0:1], 0, v51, s[0:1]
	v_pk_fma_f32 v[50:51], v[16:17], v[28:29], v[76:77] op_sel_hi:[1,0,1]
	ds_read_b128 v[14:17], v80 offset:112
	v_pk_fma_f32 v[18:19], v[32:33], v[18:19], v[48:49] op_sel:[0,1,0]
	v_pk_fma_f32 v[48:49], v[34:35], v[28:29], v[50:51] op_sel:[0,1,0]
	v_pk_fma_f32 v[28:29], v[32:33], v[28:29], v[52:53] op_sel:[0,1,0]
	v_pk_fma_f32 v[50:51], v[34:35], v[24:25], v[70:71] op_sel:[0,1,0]
	v_pk_fma_f32 v[52:53], v[32:33], v[24:25], v[72:73] op_sel:[0,1,0]
	global_load_dwordx4 v[22:25], v[22:23], off nt
	s_nop 0
	global_load_dwordx4 v[32:35], v[44:45], off nt
	v_mov_b32_e32 v72, v31
	v_mov_b32_e32 v70, v21
	s_waitcnt vmcnt(1)
	v_pk_fma_f32 v[48:49], v[24:25], v[30:31], v[48:49] op_sel_hi:[1,0,1]
	v_pk_fma_f32 v[30:31], v[22:23], v[30:31], v[28:29] op_sel_hi:[1,0,1]
	v_pk_fma_f32 v[74:75], v[24:25], v[26:27], v[50:51] op_sel_hi:[1,0,1]
	v_pk_fma_f32 v[76:77], v[22:23], v[26:27], v[52:53] op_sel_hi:[1,0,1]
	global_load_dwordx4 v[26:29], v[36:37], off nt
	global_load_dwordx4 v[50:53], v[38:39], off nt
	v_pk_fma_f32 v[44:45], v[24:25], v[20:21], v[46:47] op_sel_hi:[1,0,1]
	v_pk_fma_f32 v[46:47], v[22:23], v[20:21], v[18:19] op_sel_hi:[1,0,1]
	s_waitcnt vmcnt(2)
; #define GAS __attribute__((address_space(1)))
; #define LAS __attribute__((address_space(3)))
; __device__ __forceinline__ void p0_phase(const Args& a, LAS unsigned char* lds) {
;     ...
;                 for (int r = 0; r < 256; ++r) {
;                     const f32x4 w = *(const GAS f32x4*)(wp + (size_t)r * (3 * D));
;                     const int k = ks * 256 + r;
;                     a0 += w * sc[k]; a1 += w * sc[D + k]; a2 += w * sc[2 * D + k];
;                 }
;                 LAS float* rp = red + (ks * 24 + cg) * 12;
;                 *(LAS f32x4*)(rp) = a0; *(LAS f32x4*)(rp + 4) = a1; *(LAS f32x4*)(rp + 8) = a2;
;             }
;             __syncthreads();
;             if (tid < 288) {
;                 const int j = tid / 96, col = tid % 96, cg = col >> 2, e = col & 3;
;                 float s = 0.f;
; #pragma unroll
;                 for (int ks = 0; ks < 16; ++ks) s += red[(ks * 24 + cg) * 12 + j * 4 + e];
;                 modv[((size_t)l * 3 + j) * (3 * D) + cb + col] = s + a.in[I_MODB][(size_t)l * 3 * D + cb + col];
	v_pk_fma_f32 v[36:37], v[34:35], v[70:71], v[44:45] op_sel_hi:[1,0,1]
	v_pk_fma_f32 v[70:71], v[32:33], v[70:71], v[46:47] op_sel_hi:[1,0,1]
	v_pk_fma_f32 v[84:85], v[34:35], v[72:73], v[48:49] op_sel_hi:[1,0,1]
	global_load_dwordx4 v[46:49], v[40:41], off nt
	ds_read_b128 v[18:21], v80 offset:16496
	ds_read_b128 v[22:25], v80 offset:32880
	v_pk_fma_f32 v[72:73], v[32:33], v[72:73], v[30:31] op_sel_hi:[1,0,1]
	v_pk_fma_f32 v[76:77], v[32:33], v[82:83], v[76:77] op_sel_hi:[1,0,1]
	global_load_dwordx4 v[42:45], v[42:43], off nt
	s_nop 0
	global_load_dwordx4 v[38:41], v[62:63], off nt
	global_load_dwordx4 v[30:33], v[68:69], off nt
	v_pk_fma_f32 v[34:35], v[34:35], v[82:83], v[74:75] op_sel_hi:[1,0,1]
	v_add_u32_e32 v80, 0x80, v80
	s_waitcnt vmcnt(5) lgkmcnt(5)
	v_pk_fma_f32 v[62:63], v[28:29], v[6:7], v[36:37] op_sel_hi:[1,0,1]
	v_pk_fma_f32 v[68:69], v[26:27], v[6:7], v[70:71] op_sel_hi:[1,0,1]
	s_waitcnt lgkmcnt(4)
	v_pk_fma_f32 v[70:71], v[28:29], v[10:11], v[84:85] op_sel_hi:[1,0,1]
	v_pk_fma_f32 v[72:73], v[26:27], v[10:11], v[72:73] op_sel_hi:[1,0,1]
	s_waitcnt lgkmcnt(3)
	v_pk_fma_f32 v[74:75], v[28:29], v[2:3], v[34:35] op_sel_hi:[1,0,1]
	v_pk_fma_f32 v[76:77], v[26:27], v[2:3], v[76:77] op_sel_hi:[1,0,1]
	global_load_dwordx4 v[34:37], v[64:65], off nt
	global_load_dwordx4 v[26:29], v[66:67], off nt
	s_waitcnt vmcnt(6)
	v_pk_fma_f32 v[62:63], v[52:53], v[6:7], v[62:63] op_sel:[0,1,0]
	v_pk_fma_f32 v[64:65], v[50:51], v[6:7], v[68:69] op_sel:[0,1,0]
	v_pk_fma_f32 v[66:67], v[52:53], v[10:11], v[70:71] op_sel:[0,1,0]
	v_pk_fma_f32 v[70:71], v[50:51], v[10:11], v[72:73] op_sel:[0,1,0]
	v_pk_fma_f32 v[6:7], v[52:53], v[2:3], v[74:75] op_sel:[0,1,0]
	v_pk_fma_f32 v[2:3], v[50:51], v[2:3], v[76:77] op_sel:[0,1,0]
	v_mov_b32_e32 v10, v9
	v_mov_b32_e32 v50, v13
	s_waitcnt vmcnt(5)
	v_pk_fma_f32 v[52:53], v[48:49], v[8:9], v[62:63] op_sel_hi:[1,0,1]
	v_pk_fma_f32 v[62:63], v[46:47], v[8:9], v[64:65] op_sel_hi:[1,0,1]
	v_mov_b32_e32 v64, v5
	v_pk_fma_f32 v[68:69], v[48:49], v[12:13], v[66:67] op_sel_hi:[1,0,1]
	v_pk_fma_f32 v[70:71], v[46:47], v[12:13], v[70:71] op_sel_hi:[1,0,1]
	v_pk_fma_f32 v[6:7], v[48:49], v[4:5], v[6:7] op_sel_hi:[1,0,1]
	v_pk_fma_f32 v[2:3], v[46:47], v[4:5], v[2:3] op_sel_hi:[1,0,1]
	s_waitcnt vmcnt(4)
	v_pk_fma_f32 v[4:5], v[44:45], v[10:11], v[52:53] op_sel_hi:[1,0,1]
	v_pk_fma_f32 v[10:11], v[42:43], v[10:11], v[62:63] op_sel_hi:[1,0,1]
	v_pk_fma_f32 v[46:47], v[44:45], v[50:51], v[68:69] op_sel_hi:[1,0,1]
	v_pk_fma_f32 v[48:49], v[42:43], v[50:51], v[70:71] op_sel_hi:[1,0,1]
	v_pk_fma_f32 v[6:7], v[44:45], v[64:65], v[6:7] op_sel_hi:[1,0,1]
	v_pk_fma_f32 v[2:3], v[42:43], v[64:65], v[2:3] op_sel_hi:[1,0,1]
	s_waitcnt vmcnt(3) lgkmcnt(2)
	v_pk_fma_f32 v[4:5], v[40:41], v[14:15], v[4:5] op_sel_hi:[1,0,1]
	v_pk_fma_f32 v[10:11], v[38:39], v[14:15], v[10:11] op_sel_hi:[1,0,1]
	s_waitcnt lgkmcnt(1)
	v_pk_fma_f32 v[42:43], v[40:41], v[18:19], v[46:47] op_sel_hi:[1,0,1]
	v_pk_fma_f32 v[44:45], v[38:39], v[18:19], v[48:49] op_sel_hi:[1,0,1]
	s_waitcnt lgkmcnt(0)
	v_pk_fma_f32 v[6:7], v[40:41], v[22:23], v[6:7] op_sel_hi:[1,0,1]
	v_pk_fma_f32 v[2:3], v[38:39], v[22:23], v[2:3] op_sel_hi:[1,0,1]
	s_waitcnt vmcnt(2)
	v_pk_fma_f32 v[4:5], v[32:33], v[14:15], v[4:5] op_sel:[0,1,0]
	v_pk_fma_f32 v[10:11], v[30:31], v[14:15], v[10:11] op_sel:[0,1,0]
	v_pk_fma_f32 v[14:15], v[32:33], v[18:19], v[42:43] op_sel:[0,1,0]
	v_pk_fma_f32 v[18:19], v[30:31], v[18:19], v[44:45] op_sel:[0,1,0]
	v_pk_fma_f32 v[6:7], v[32:33], v[22:23], v[6:7] op_sel:[0,1,0]
	v_pk_fma_f32 v[2:3], v[30:31], v[22:23], v[2:3] op_sel:[0,1,0]
	v_mov_b32_e32 v8, v17
	v_mov_b32_e32 v12, v21
	v_mov_b32_e32 v66, v25
	s_waitcnt vmcnt(1)
	v_pk_fma_f32 v[4:5], v[36:37], v[16:17], v[4:5] op_sel_hi:[1,0,1]
	v_pk_fma_f32 v[10:11], v[34:35], v[16:17], v[10:11] op_sel_hi:[1,0,1]
	v_pk_fma_f32 v[14:15], v[36:37], v[20:21], v[14:15] op_sel_hi:[1,0,1]
	v_pk_fma_f32 v[16:17], v[34:35], v[20:21], v[18:19] op_sel_hi:[1,0,1]
	v_pk_fma_f32 v[6:7], v[36:37], v[24:25], v[6:7] op_sel_hi:[1,0,1]
	v_pk_fma_f32 v[2:3], v[34:35], v[24:25], v[2:3] op_sel_hi:[1,0,1]
	s_waitcnt vmcnt(0)
	v_pk_fma_f32 v[32:33], v[28:29], v[8:9], v[4:5] op_sel_hi:[1,0,1]
	v_pk_fma_f32 v[30:31], v[26:27], v[8:9], v[10:11] op_sel_hi:[1,0,1]
	v_pk_fma_f32 v[36:37], v[28:29], v[12:13], v[14:15] op_sel_hi:[1,0,1]
	v_pk_fma_f32 v[34:35], v[26:27], v[12:13], v[16:17] op_sel_hi:[1,0,1]
	v_pk_fma_f32 v[44:45], v[28:29], v[66:67], v[6:7] op_sel_hi:[1,0,1]
	v_pk_fma_f32 v[42:43], v[26:27], v[66:67], v[2:3] op_sel_hi:[1,0,1]
	s_cbranch_scc0 .LBB0_18
	ds_write_b128 v79, v[30:33] offset:49152
	ds_write_b128 v79, v[34:37] offset:49168
	ds_write_b128 v79, v[42:45] offset:49184
.LBB0_20:
	s_or_b64 exec, exec, s[8:9]
	s_waitcnt lgkmcnt(0)
	s_barrier
	s_and_saveexec_b64 s[0:1], s[4:5]
	s_cbranch_execz .LBB0_15
	s_and_b32 s6, s22, 0x7f
	s_mul_i32 s9, s23, 0xc000
	s_mul_hi_i32 s8, s23, 0xc000
	s_add_u32 s9, s62, s9
	s_addc_u32 s16, s63, s8
	s_mulk_i32 s6, 0x180
	s_add_u32 s8, s9, s6
	s_addc_u32 s9, s16, 0
	v_lshl_add_u64 v[2:3], s[8:9], 0, v[58:59]
	global_load_dword v6, v[2:3], off nt
	v_mad_u64_u32 v[2:3], s[8:9], s23, 3, v[54:55]
	v_mov_b64_e32 v[4:5], s[12:13]
	ds_read_b32 v7, v55 offset:49152
	ds_read_b32 v8, v55 offset:50304
	ds_read_b32 v9, v55 offset:51456
	ds_read_b32 v10, v55 offset:52608
	ds_read_b32 v11, v55 offset:53760
	ds_read_b32 v12, v55 offset:54912
	ds_read_b32 v13, v55 offset:56064
	ds_read_b32 v14, v55 offset:57216
	ds_read_b32 v15, v55 offset:58368
	ds_read_b32 v16, v55 offset:59520
	ds_read_b32 v17, v55 offset:60672
	ds_read_b32 v18, v55 offset:61824
	ds_read_b32 v19, v55 offset:62976
	ds_read_b32 v20, v55 offset:64128
	ds_read_b32 v21, v55 offset:65280
	ds_read_b32 v22, v78 offset:17280
	v_mad_i64_i32 v[2:3], s[8:9], v2, s11, v[4:5]
	s_waitcnt lgkmcnt(14)
	v_add_f32_e32 v4, 0, v7
	v_add_f32_e32 v4, v4, v8
	s_waitcnt lgkmcnt(13)
	v_add_f32_e32 v4, v4, v9
	s_waitcnt lgkmcnt(12)
	v_add_f32_e32 v4, v4, v10
	s_waitcnt lgkmcnt(11)
	v_add_f32_e32 v4, v4, v11
	s_waitcnt lgkmcnt(10)
	v_add_f32_e32 v4, v4, v12
	s_waitcnt lgkmcnt(9)
	v_add_f32_e32 v4, v4, v13
	s_waitcnt lgkmcnt(8)
	v_add_f32_e32 v4, v4, v14
	s_waitcnt lgkmcnt(7)
	v_add_f32_e32 v4, v4, v15
	s_waitcnt lgkmcnt(6)
	v_add_f32_e32 v4, v4, v16
	s_waitcnt lgkmcnt(5)
	v_add_f32_e32 v4, v4, v17
	s_waitcnt lgkmcnt(4)
	v_add_f32_e32 v4, v4, v18
	s_waitcnt lgkmcnt(3)
	v_add_f32_e32 v4, v4, v19
	s_waitcnt lgkmcnt(2)
	v_add_f32_e32 v4, v4, v20
	s_waitcnt lgkmcnt(1)
	v_add_f32_e32 v4, v4, v21
	v_lshl_add_u64 v[2:3], v[2:3], 0, s[6:7]
	s_waitcnt lgkmcnt(0)
	v_add_f32_e32 v4, v4, v22
	v_lshl_add_u64 v[2:3], v[2:3], 0, v[58:59]
	s_waitcnt vmcnt(0)
	v_add_f32_e32 v4, v4, v6
	global_store_dword v[2:3], v4, off
	s_branch .LBB0_15

; __device__ __forceinline__ void tr_load(const float* W, int N, int mat, int item, int lane, int nblk, float (&x)[32]) {
;     const int kb = item / nblk, nb = item % nblk, k0 = 64 * kb, n0 = 32 * nb;
;     const int sc = src_col(mat, n0 + (lane & 31));
; #pragma unroll
;     for (int i = 0; i < 32; ++i) { const int kk = 2 * i + (lane >> 5); x[i] = sc >= 0 ? W[(size_t)(k0 + kk) * N + sc] : 0.f; }
; }
.LBB0_42:
	v_mov_b32_e32 v5, 0
	v_lshl_add_u64 v[26:27], v[2:3], 0, v[4:5]
	v_lshl_add_u64 v[4:5], v[26:27], 0, s[58:59]
	v_lshl_add_u64 v[6:7], v[26:27], 0, s[34:35]
	v_lshl_add_u64 v[8:9], v[26:27], 0, s[54:55]
	v_lshl_add_u64 v[10:11], v[26:27], 0, s[22:23]
	v_lshl_add_u64 v[12:13], v[26:27], 0, s[20:21]
	v_lshl_add_u64 v[14:15], v[26:27], 0, s[18:19]
	v_lshl_add_u64 v[16:17], v[26:27], 0, s[16:17]
	global_load_dword v2, v[26:27], off nt
	global_load_dword v3, v[4:5], off nt
	s_nop 0
	global_load_dword v4, v[6:7], off nt
	global_load_dword v5, v[8:9], off nt
	s_nop 0
	global_load_dword v6, v[10:11], off nt
	global_load_dword v7, v[12:13], off nt
	global_load_dword v8, v[14:15], off nt
	global_load_dword v9, v[16:17], off nt
	v_lshl_add_u64 v[10:11], v[26:27], 0, s[8:9]
	v_lshl_add_u64 v[12:13], v[26:27], 0, s[6:7]
	v_lshl_add_u64 v[14:15], v[26:27], 0, s[0:1]
	v_lshl_add_u64 v[16:17], v[26:27], 0, s[24:25]
	v_lshl_add_u64 v[18:19], v[26:27], 0, s[94:95]
	v_lshl_add_u64 v[20:21], v[26:27], 0, s[14:15]
	v_lshl_add_u64 v[22:23], v[26:27], 0, s[96:97]
	v_lshl_add_u64 v[24:25], v[26:27], 0, s[90:91]
	global_load_dword v10, v[10:11], off nt
	s_nop 0
	global_load_dword v11, v[12:13], off nt
	s_nop 0
	global_load_dword v12, v[14:15], off nt
	global_load_dword v13, v[16:17], off nt
	s_nop 0
	global_load_dword v14, v[18:19], off nt
	global_load_dword v15, v[20:21], off nt
	global_load_dword v16, v[22:23], off nt
	global_load_dword v17, v[24:25], off nt
	v_lshl_add_u64 v[18:19], v[26:27], 0, s[88:89]
	v_lshl_add_u64 v[20:21], v[26:27], 0, s[86:87]
	v_lshl_add_u64 v[22:23], v[26:27], 0, s[84:85]
	v_lshl_add_u64 v[24:25], v[26:27], 0, s[50:51]
	v_lshl_add_u64 v[28:29], v[26:27], 0, vcc
	v_lshl_add_u64 v[30:31], v[26:27], 0, s[62:63]
	v_lshl_add_u64 v[32:33], v[26:27], 0, s[60:61]
	v_lshl_add_u64 v[34:35], v[26:27], 0, s[48:49]
	global_load_dword v18, v[18:19], off nt
	s_nop 0
	global_load_dword v19, v[20:21], off nt
	s_nop 0
	global_load_dword v20, v[22:23], off nt
	global_load_dword v21, v[24:25], off nt
	s_nop 0
	global_load_dword v22, v[28:29], off nt
	global_load_dword v23, v[30:31], off nt
	global_load_dword v24, v[32:33], off nt
	global_load_dword v25, v[34:35], off nt
	v_lshl_add_u64 v[28:29], v[26:27], 0, s[46:47]
	v_lshl_add_u64 v[30:31], v[26:27], 0, s[44:45]
	v_lshl_add_u64 v[32:33], v[26:27], 0, s[42:43]
	v_lshl_add_u64 v[34:35], v[26:27], 0, s[40:41]
	v_lshl_add_u64 v[36:37], v[26:27], 0, s[38:39]
	v_lshl_add_u64 v[38:39], v[26:27], 0, s[36:37]
	v_lshl_add_u64 v[40:41], v[26:27], 0, s[30:31]
	v_lshl_add_u64 v[42:43], v[26:27], 0, s[26:27]
	global_load_dword v26, v[28:29], off nt
	global_load_dword v27, v[30:31], off nt
	s_nop 0
	global_load_dword v28, v[32:33], off nt
	global_load_dword v29, v[34:35], off nt
	global_load_dword v30, v[36:37], off nt
	global_load_dword v31, v[38:39], off nt
	s_nop 0
	global_load_dword v32, v[40:41], off nt
	global_load_dword v33, v[42:43], off nt
	v_readlane_b32 s84, v254, 56
	v_readlane_b32 s96, v254, 52
	v_readlane_b32 s30, v254, 54
	v_readlane_b32 s88, v254, 58
	v_readlane_b32 s85, v254, 57
	s_mov_b32 s48, s84
	v_readlane_b32 s97, v254, 53
	v_readlane_b32 s31, v254, 55
	v_readlane_b32 s89, v254, 59
	s_branch .LBB0_44
; __device__ __forceinline__ void tr_load(const float* W, int N, int mat, int item, int lane, int nblk, float (&x)[32]) {
;     const int kb = item / nblk, nb = item % nblk, k0 = 64 * kb, n0 = 32 * nb;
;     const int sc = src_col(mat, n0 + (lane & 31));
; #pragma unroll
;     for (int i = 0; i < 32; ++i) { const int kk = 2 * i + (lane >> 5); x[i] = sc >= 0 ? W[(size_t)(k0 + kk) * N + sc] : 0.f; }
; }
.LBB0_43:
	s_add_i32 s0, s71, 0x9400
	s_lshl_b32 s1, s71, 5
	s_lshr_b32 s0, s0, 1
	s_and_b32 s1, s1, 0xfe0
	s_and_b32 s0, s0, 0x7fc0
	v_and_or_b32 v1, v98, 31, s1
	s_waitcnt vmcnt(31)
	v_lshrrev_b32_e32 v2, 5, v99
	v_readlane_b32 s72, v254, 20
	s_waitcnt vmcnt(27)
	v_or_b32_e32 v6, s0, v2
	v_lshlrev_b32_e32 v2, 2, v1
	v_mov_b32_e32 v3, 0
	v_readlane_b32 s73, v254, 21
	s_mov_b32 s0, 0x8000
	v_readlane_b32 s74, v254, 22
	v_lshl_add_u64 v[4:5], s[72:73], 0, v[2:3]
	v_lshlrev_b32_e32 v2, 14, v6
	s_waitcnt vmcnt(6)
	v_lshl_add_u64 v[26:27], v[4:5], 0, v[2:3]
	v_add_co_u32_e32 v4, vcc, s0, v26
	s_mov_b32 s0, 0x10000
	s_nop 0
	v_addc_co_u32_e32 v5, vcc, 0, v27, vcc
	v_add_co_u32_e32 v6, vcc, s0, v26
	s_mov_b32 s0, 0x18000
	s_nop 0
	v_addc_co_u32_e32 v7, vcc, 0, v27, vcc
	v_add_co_u32_e32 v8, vcc, s0, v26
	s_mov_b32 s0, 0x20000
	s_nop 0
	v_addc_co_u32_e32 v9, vcc, 0, v27, vcc
	v_add_co_u32_e32 v10, vcc, s0, v26
	s_mov_b32 s0, 0x28000
	s_nop 0
	v_addc_co_u32_e32 v11, vcc, 0, v27, vcc
	v_add_co_u32_e32 v12, vcc, s0, v26
	s_mov_b32 s0, 0x30000
	s_nop 0
	v_addc_co_u32_e32 v13, vcc, 0, v27, vcc
	v_add_co_u32_e32 v14, vcc, s0, v26
	s_mov_b32 s0, 0x38000
	s_nop 0
	v_addc_co_u32_e32 v15, vcc, 0, v27, vcc
	v_add_co_u32_e32 v16, vcc, s0, v26
	s_mov_b32 s0, 0x40000
	s_nop 0
	v_addc_co_u32_e32 v17, vcc, 0, v27, vcc
	global_load_dword v2, v[26:27], off nt
	global_load_dword v3, v[4:5], off nt
	s_nop 0
	global_load_dword v4, v[6:7], off nt
	global_load_dword v5, v[8:9], off nt
	s_nop 0
	global_load_dword v6, v[10:11], off nt
	global_load_dword v7, v[12:13], off nt
	global_load_dword v8, v[14:15], off nt
	global_load_dword v9, v[16:17], off nt
	v_add_co_u32_e32 v10, vcc, s0, v26
	s_mov_b32 s0, 0x48000
	s_nop 0
	v_addc_co_u32_e32 v11, vcc, 0, v27, vcc
	v_add_co_u32_e32 v12, vcc, s0, v26
	s_mov_b32 s0, 0x50000
	s_nop 0
	v_addc_co_u32_e32 v13, vcc, 0, v27, vcc
	v_add_co_u32_e32 v14, vcc, s0, v26
	s_mov_b32 s0, 0x58000
	s_nop 0
	v_addc_co_u32_e32 v15, vcc, 0, v27, vcc
	v_add_co_u32_e32 v16, vcc, s0, v26
	s_mov_b32 s0, 0x60000
	s_nop 0
	v_addc_co_u32_e32 v17, vcc, 0, v27, vcc
	v_add_co_u32_e32 v18, vcc, s0, v26
	s_mov_b32 s0, 0x68000
	s_nop 0
	v_addc_co_u32_e32 v19, vcc, 0, v27, vcc
	v_add_co_u32_e32 v20, vcc, s0, v26
	s_mov_b32 s0, 0x70000
	s_nop 0
	v_addc_co_u32_e32 v21, vcc, 0, v27, vcc
	v_add_co_u32_e32 v22, vcc, s0, v26
	s_mov_b32 s0, 0x78000
	s_nop 0
	v_addc_co_u32_e32 v23, vcc, 0, v27, vcc
	v_add_co_u32_e32 v24, vcc, s0, v26
	s_mov_b32 s0, 0x80000
	s_nop 0
	v_addc_co_u32_e32 v25, vcc, 0, v27, vcc
	global_load_dword v10, v[10:11], off nt
	s_nop 0
	global_load_dword v11, v[12:13], off nt
	s_nop 0
	global_load_dword v12, v[14:15], off nt
	global_load_dword v13, v[16:17], off nt
	s_nop 0
	global_load_dword v14, v[18:19], off nt
	global_load_dword v15, v[20:21], off nt
	global_load_dword v16, v[22:23], off nt
	global_load_dword v17, v[24:25], off nt
	v_add_co_u32_e32 v18, vcc, s0, v26
	s_mov_b32 s0, 0x88000
	s_nop 0
	v_addc_co_u32_e32 v19, vcc, 0, v27, vcc
	v_add_co_u32_e32 v20, vcc, s0, v26
	s_mov_b32 s0, 0x90000
	s_nop 0
	v_addc_co_u32_e32 v21, vcc, 0, v27, vcc
	v_add_co_u32_e32 v22, vcc, s0, v26
	s_mov_b32 s0, 0x98000
	s_nop 0
	v_addc_co_u32_e32 v23, vcc, 0, v27, vcc
	v_add_co_u32_e32 v24, vcc, s0, v26
	s_mov_b32 s0, 0xa0000
	s_nop 0
	v_addc_co_u32_e32 v25, vcc, 0, v27, vcc
	s_waitcnt vmcnt(21)
	v_add_co_u32_e32 v28, vcc, s0, v26
	s_mov_b32 s0, 0xa8000
	s_waitcnt vmcnt(20)
	v_addc_co_u32_e32 v29, vcc, 0, v27, vcc
	s_waitcnt vmcnt(19)
	v_add_co_u32_e32 v30, vcc, s0, v26
	s_mov_b32 s0, 0xb0000
	s_waitcnt vmcnt(18)
	v_addc_co_u32_e32 v31, vcc, 0, v27, vcc
	s_waitcnt vmcnt(17)
	v_add_co_u32_e32 v32, vcc, s0, v26
	s_mov_b32 s0, 0xb8000
	s_waitcnt vmcnt(16)
	v_addc_co_u32_e32 v33, vcc, 0, v27, vcc
	v_add_co_u32_e32 v34, vcc, s0, v26
	s_mov_b32 s0, 0xc0000
	s_nop 0
	v_addc_co_u32_e32 v35, vcc, 0, v27, vcc
	global_load_dword v18, v[18:19], off nt
	s_nop 0
	global_load_dword v19, v[20:21], off nt
	s_nop 0
	global_load_dword v20, v[22:23], off nt
	global_load_dword v21, v[24:25], off nt
	s_nop 0
	global_load_dword v22, v[28:29], off nt
	global_load_dword v23, v[30:31], off nt
	global_load_dword v24, v[32:33], off nt
	global_load_dword v25, v[34:35], off nt
	v_add_co_u32_e32 v28, vcc, s0, v26
	s_mov_b32 s0, 0xc8000
	s_nop 0
	v_addc_co_u32_e32 v29, vcc, 0, v27, vcc
	v_add_co_u32_e32 v30, vcc, s0, v26
	s_mov_b32 s0, 0xd0000
	s_nop 0
	v_addc_co_u32_e32 v31, vcc, 0, v27, vcc
	v_add_co_u32_e32 v32, vcc, s0, v26
	s_mov_b32 s0, 0xd8000
	s_nop 0
	v_addc_co_u32_e32 v33, vcc, 0, v27, vcc
	v_add_co_u32_e32 v34, vcc, s0, v26
	s_mov_b32 s0, 0xe0000
	s_nop 0
	v_addc_co_u32_e32 v35, vcc, 0, v27, vcc
	v_add_co_u32_e32 v36, vcc, s0, v26
	s_mov_b32 s0, 0xe8000
	s_nop 0
	v_addc_co_u32_e32 v37, vcc, 0, v27, vcc
	v_add_co_u32_e32 v38, vcc, s0, v26
	v_readlane_b32 s75, v254, 23
	s_nop 0
	v_addc_co_u32_e32 v39, vcc, 0, v27, vcc
	v_add_co_u32_e32 v40, vcc, 0xf0000, v26
	v_readlane_b32 s76, v254, 24
	s_nop 0
	v_addc_co_u32_e32 v41, vcc, 0, v27, vcc
	v_add_co_u32_e32 v42, vcc, 0xf8000, v26
	v_readlane_b32 s77, v254, 25
	s_nop 0
	v_addc_co_u32_e32 v43, vcc, 0, v27, vcc
	global_load_dword v26, v[28:29], off nt
	global_load_dword v27, v[30:31], off nt
	s_nop 0
	global_load_dword v28, v[32:33], off nt
	global_load_dword v29, v[34:35], off nt
	global_load_dword v30, v[36:37], off nt
	global_load_dword v31, v[38:39], off nt
	s_nop 0
	global_load_dword v32, v[40:41], off nt
	global_load_dword v33, v[42:43], off nt
	v_readlane_b32 s78, v254, 26
	v_readlane_b32 s79, v254, 27
	v_readlane_b32 s80, v254, 28
	v_readlane_b32 s81, v254, 29
	v_readlane_b32 s82, v254, 30
	v_readlane_b32 s83, v254, 31
	v_readlane_b32 s84, v254, 32
	v_readlane_b32 s85, v254, 33
	v_readlane_b32 s86, v254, 34
	v_readlane_b32 s87, v254, 35

; __device__ __forceinline__ void tr_load(const float* W, int N, int mat, int item, int lane, int nblk, float (&x)[32]) {
;     const int kb = item / nblk, nb = item % nblk, k0 = 64 * kb, n0 = 32 * nb;
;     const int sc = src_col(mat, n0 + (lane & 31));
; #pragma unroll
;     for (int i = 0; i < 32; ++i) { const int kk = 2 * i + (lane >> 5); x[i] = sc >= 0 ? W[(size_t)(k0 + kk) * N + sc] : 0.f; }
; }
.LBB0_53:
	s_or_b64 exec, exec, s[0:1]
	v_lshrrev_b32_e32 v1, 5, v99
	s_waitcnt vmcnt(30)
	v_mov_b32_e32 v3, 0
	v_cmp_gt_i32_e32 vcc, 0, v2
	v_cmp_lt_i32_e64 s[0:1], -1, v2
	v_lshl_or_b32 v1, s8, 6, v1
	v_lshl_add_u64 v[100:101], v[2:3], 2, s[66:67]
	v_mov_b32_e32 v2, v3
	s_and_saveexec_b64 s[6:7], s[0:1]
	s_cbranch_execz .LBB0_55
	s_mov_b32 s8, 0xd600
	v_mad_i64_i32 v[2:3], s[0:1], v1, s8, v[100:101]
	s_waitcnt vmcnt(29)
	v_or_b32_e32 v4, 2, v1
	s_waitcnt vmcnt(28)
	v_mad_i64_i32 v[4:5], s[0:1], v4, s8, v[100:101]
	global_load_dword v2, v[2:3], off nt
	s_nop 0
	global_load_dword v3, v[4:5], off nt

; __device__ __forceinline__ void tr_load(const float* W, int N, int mat, int item, int lane, int nblk, float (&x)[32]) {
;     const int kb = item / nblk, nb = item % nblk, k0 = 64 * kb, n0 = 32 * nb;
;     const int sc = src_col(mat, n0 + (lane & 31));
; #pragma unroll
;     for (int i = 0; i < 32; ++i) { const int kk = 2 * i + (lane >> 5); x[i] = sc >= 0 ? W[(size_t)(k0 + kk) * N + sc] : 0.f; }
; }
.LBB0_58:
	s_waitcnt vmcnt(29)
	v_or_b32_e32 v4, 4, v1
	s_mov_b32 s8, 0xd600
	v_mad_i64_i32 v[34:35], s[6:7], v4, s8, v[100:101]
	v_or_b32_e32 v4, 6, v1
	v_mad_i64_i32 v[36:37], s[6:7], v4, s8, v[100:101]
	global_load_dword v4, v[34:35], off nt
	global_load_dword v66, v[36:37], off nt
	s_waitcnt vmcnt(1)
	v_mov_b64_e32 v[64:65], v[32:33]
	v_mov_b64_e32 v[36:37], v[4:5]
	v_mov_b64_e32 v[62:63], v[30:31]
	v_mov_b64_e32 v[60:61], v[28:29]
	v_mov_b64_e32 v[58:59], v[26:27]
	v_mov_b64_e32 v[56:57], v[24:25]
	v_mov_b64_e32 v[54:55], v[22:23]
	v_mov_b64_e32 v[52:53], v[20:21]
	v_mov_b64_e32 v[50:51], v[18:19]
	v_mov_b64_e32 v[48:49], v[16:17]
	v_mov_b64_e32 v[46:47], v[14:15]
	v_mov_b64_e32 v[44:45], v[12:13]
	v_mov_b64_e32 v[42:43], v[10:11]
	v_mov_b64_e32 v[40:41], v[8:9]
	v_mov_b64_e32 v[38:39], v[6:7]
	v_mov_b64_e32 v[34:35], v[2:3]
	s_waitcnt vmcnt(0)
	v_mov_b32_e32 v37, v66

; __device__ __forceinline__ void tr_load(const float* W, int N, int mat, int item, int lane, int nblk, float (&x)[32]) {
;     const int kb = item / nblk, nb = item % nblk, k0 = 64 * kb, n0 = 32 * nb;
;     const int sc = src_col(mat, n0 + (lane & 31));
; #pragma unroll
;     for (int i = 0; i < 32; ++i) { const int kk = 2 * i + (lane >> 5); x[i] = sc >= 0 ? W[(size_t)(k0 + kk) * N + sc] : 0.f; }
; }
.LBB0_62:
	s_waitcnt vmcnt(1)
	v_or_b32_e32 v2, 8, v1
	s_mov_b32 s8, 0xd600
	s_waitcnt vmcnt(0)
	v_mad_i64_i32 v[2:3], s[6:7], v2, s8, v[100:101]
	v_or_b32_e32 v4, 10, v1
	v_mad_i64_i32 v[4:5], s[6:7], v4, s8, v[100:101]
	global_load_dword v38, v[2:3], off nt
	global_load_dword v66, v[4:5], off nt
	s_waitcnt vmcnt(1)
	v_mov_b64_e32 v[2:3], v[34:35]
	v_mov_b64_e32 v[6:7], v[38:39]
	v_mov_b64_e32 v[4:5], v[36:37]
	v_mov_b64_e32 v[8:9], v[40:41]
	v_mov_b64_e32 v[10:11], v[42:43]
	v_mov_b64_e32 v[12:13], v[44:45]
	v_mov_b64_e32 v[14:15], v[46:47]
	v_mov_b64_e32 v[16:17], v[48:49]
	v_mov_b64_e32 v[18:19], v[50:51]
	v_mov_b64_e32 v[20:21], v[52:53]
	v_mov_b64_e32 v[22:23], v[54:55]
	v_mov_b64_e32 v[24:25], v[56:57]
	v_mov_b64_e32 v[26:27], v[58:59]
	v_mov_b64_e32 v[28:29], v[60:61]
	v_mov_b64_e32 v[30:31], v[62:63]
	v_mov_b64_e32 v[32:33], v[64:65]
	s_waitcnt vmcnt(0)
	v_mov_b32_e32 v7, v66

; __device__ __forceinline__ void tr_load(const float* W, int N, int mat, int item, int lane, int nblk, float (&x)[32]) {
;     const int kb = item / nblk, nb = item % nblk, k0 = 64 * kb, n0 = 32 * nb;
;     const int sc = src_col(mat, n0 + (lane & 31));
; #pragma unroll
;     for (int i = 0; i < 32; ++i) { const int kk = 2 * i + (lane >> 5); x[i] = sc >= 0 ? W[(size_t)(k0 + kk) * N + sc] : 0.f; }
; }
.LBB0_66:
	s_waitcnt vmcnt(25)
	v_or_b32_e32 v8, 12, v1
	s_mov_b32 s8, 0xd600
	v_mad_i64_i32 v[34:35], s[6:7], v8, s8, v[100:101]
	v_or_b32_e32 v8, 14, v1
	v_mad_i64_i32 v[36:37], s[6:7], v8, s8, v[100:101]
	global_load_dword v8, v[34:35], off nt
	global_load_dword v66, v[36:37], off nt
	s_waitcnt vmcnt(1)
	v_mov_b64_e32 v[64:65], v[32:33]
	v_mov_b64_e32 v[40:41], v[8:9]
	v_mov_b64_e32 v[62:63], v[30:31]
	v_mov_b64_e32 v[60:61], v[28:29]
	v_mov_b64_e32 v[58:59], v[26:27]
	v_mov_b64_e32 v[56:57], v[24:25]
	v_mov_b64_e32 v[54:55], v[22:23]
	v_mov_b64_e32 v[52:53], v[20:21]
	v_mov_b64_e32 v[50:51], v[18:19]
	v_mov_b64_e32 v[48:49], v[16:17]
	v_mov_b64_e32 v[46:47], v[14:15]
	v_mov_b64_e32 v[44:45], v[12:13]
	v_mov_b64_e32 v[42:43], v[10:11]
	v_mov_b64_e32 v[38:39], v[6:7]
	v_mov_b64_e32 v[36:37], v[4:5]
	v_mov_b64_e32 v[34:35], v[2:3]
	s_waitcnt vmcnt(0)
	v_mov_b32_e32 v41, v66

; __device__ __forceinline__ void tr_load(const float* W, int N, int mat, int item, int lane, int nblk, float (&x)[32]) {
;     const int kb = item / nblk, nb = item % nblk, k0 = 64 * kb, n0 = 32 * nb;
;     const int sc = src_col(mat, n0 + (lane & 31));
; #pragma unroll
;     for (int i = 0; i < 32; ++i) { const int kk = 2 * i + (lane >> 5); x[i] = sc >= 0 ? W[(size_t)(k0 + kk) * N + sc] : 0.f; }
; }
.LBB0_70:
	s_waitcnt vmcnt(1)
	v_or_b32_e32 v2, 16, v1
	s_mov_b32 s8, 0xd600
	s_waitcnt vmcnt(0)
	v_mad_i64_i32 v[2:3], s[6:7], v2, s8, v[100:101]
	v_or_b32_e32 v4, 18, v1
	v_mad_i64_i32 v[4:5], s[6:7], v4, s8, v[100:101]
	global_load_dword v42, v[2:3], off nt
	global_load_dword v66, v[4:5], off nt
	s_waitcnt vmcnt(1)
	v_mov_b64_e32 v[2:3], v[34:35]
	v_mov_b64_e32 v[10:11], v[42:43]
	v_mov_b64_e32 v[4:5], v[36:37]
	v_mov_b64_e32 v[6:7], v[38:39]
	v_mov_b64_e32 v[8:9], v[40:41]
	v_mov_b64_e32 v[12:13], v[44:45]
	v_mov_b64_e32 v[14:15], v[46:47]
	v_mov_b64_e32 v[16:17], v[48:49]
	v_mov_b64_e32 v[18:19], v[50:51]
	v_mov_b64_e32 v[20:21], v[52:53]
	v_mov_b64_e32 v[22:23], v[54:55]
	v_mov_b64_e32 v[24:25], v[56:57]
	v_mov_b64_e32 v[26:27], v[58:59]
	v_mov_b64_e32 v[28:29], v[60:61]
	v_mov_b64_e32 v[30:31], v[62:63]
	v_mov_b64_e32 v[32:33], v[64:65]
	s_waitcnt vmcnt(0)
	v_mov_b32_e32 v11, v66

; __device__ __forceinline__ void tr_load(const float* W, int N, int mat, int item, int lane, int nblk, float (&x)[32]) {
;     const int kb = item / nblk, nb = item % nblk, k0 = 64 * kb, n0 = 32 * nb;
;     const int sc = src_col(mat, n0 + (lane & 31));
; #pragma unroll
;     for (int i = 0; i < 32; ++i) { const int kk = 2 * i + (lane >> 5); x[i] = sc >= 0 ? W[(size_t)(k0 + kk) * N + sc] : 0.f; }
; }
.LBB0_74:
	s_waitcnt vmcnt(21)
	v_or_b32_e32 v12, 20, v1
	s_mov_b32 s8, 0xd600
	v_mad_i64_i32 v[34:35], s[6:7], v12, s8, v[100:101]
	v_or_b32_e32 v12, 22, v1
	v_mad_i64_i32 v[36:37], s[6:7], v12, s8, v[100:101]
	global_load_dword v12, v[34:35], off nt
	global_load_dword v66, v[36:37], off nt
	s_waitcnt vmcnt(1)
	v_mov_b64_e32 v[64:65], v[32:33]
	v_mov_b64_e32 v[44:45], v[12:13]
	v_mov_b64_e32 v[62:63], v[30:31]
	v_mov_b64_e32 v[60:61], v[28:29]
	v_mov_b64_e32 v[58:59], v[26:27]
	v_mov_b64_e32 v[56:57], v[24:25]
	v_mov_b64_e32 v[54:55], v[22:23]
	v_mov_b64_e32 v[52:53], v[20:21]
	v_mov_b64_e32 v[50:51], v[18:19]
	v_mov_b64_e32 v[48:49], v[16:17]
	v_mov_b64_e32 v[46:47], v[14:15]
	v_mov_b64_e32 v[42:43], v[10:11]
	v_mov_b64_e32 v[40:41], v[8:9]
	v_mov_b64_e32 v[38:39], v[6:7]
	v_mov_b64_e32 v[36:37], v[4:5]
	v_mov_b64_e32 v[34:35], v[2:3]
	s_waitcnt vmcnt(0)
	v_mov_b32_e32 v45, v66

; __device__ __forceinline__ void tr_load(const float* W, int N, int mat, int item, int lane, int nblk, float (&x)[32]) {
;     const int kb = item / nblk, nb = item % nblk, k0 = 64 * kb, n0 = 32 * nb;
;     const int sc = src_col(mat, n0 + (lane & 31));
; #pragma unroll
;     for (int i = 0; i < 32; ++i) { const int kk = 2 * i + (lane >> 5); x[i] = sc >= 0 ? W[(size_t)(k0 + kk) * N + sc] : 0.f; }
; }
.LBB0_78:
	s_waitcnt vmcnt(1)
	v_or_b32_e32 v2, 24, v1
	s_mov_b32 s8, 0xd600
	s_waitcnt vmcnt(0)
	v_mad_i64_i32 v[2:3], s[6:7], v2, s8, v[100:101]
	v_or_b32_e32 v4, 26, v1
	v_mad_i64_i32 v[4:5], s[6:7], v4, s8, v[100:101]
	global_load_dword v46, v[2:3], off nt
	global_load_dword v66, v[4:5], off nt
	s_waitcnt vmcnt(1)
	v_mov_b64_e32 v[2:3], v[34:35]
	v_mov_b64_e32 v[14:15], v[46:47]
	v_mov_b64_e32 v[4:5], v[36:37]
	v_mov_b64_e32 v[6:7], v[38:39]
	v_mov_b64_e32 v[8:9], v[40:41]
	v_mov_b64_e32 v[10:11], v[42:43]
	v_mov_b64_e32 v[12:13], v[44:45]
	v_mov_b64_e32 v[16:17], v[48:49]
	v_mov_b64_e32 v[18:19], v[50:51]
	v_mov_b64_e32 v[20:21], v[52:53]
	v_mov_b64_e32 v[22:23], v[54:55]
	v_mov_b64_e32 v[24:25], v[56:57]
	v_mov_b64_e32 v[26:27], v[58:59]
	v_mov_b64_e32 v[28:29], v[60:61]
	v_mov_b64_e32 v[30:31], v[62:63]
	v_mov_b64_e32 v[32:33], v[64:65]
	s_waitcnt vmcnt(0)
	v_mov_b32_e32 v15, v66

; __device__ __forceinline__ void tr_load(const float* W, int N, int mat, int item, int lane, int nblk, float (&x)[32]) {
;     const int kb = item / nblk, nb = item % nblk, k0 = 64 * kb, n0 = 32 * nb;
;     const int sc = src_col(mat, n0 + (lane & 31));
; #pragma unroll
;     for (int i = 0; i < 32; ++i) { const int kk = 2 * i + (lane >> 5); x[i] = sc >= 0 ? W[(size_t)(k0 + kk) * N + sc] : 0.f; }
; }
.LBB0_82:
	s_waitcnt vmcnt(17)
	v_or_b32_e32 v16, 28, v1
	s_mov_b32 s8, 0xd600
	v_mad_i64_i32 v[34:35], s[6:7], v16, s8, v[100:101]
	v_or_b32_e32 v16, 30, v1
	v_mad_i64_i32 v[36:37], s[6:7], v16, s8, v[100:101]
	global_load_dword v16, v[34:35], off nt
	global_load_dword v66, v[36:37], off nt
	s_waitcnt vmcnt(1)
	v_mov_b64_e32 v[64:65], v[32:33]
	v_mov_b64_e32 v[48:49], v[16:17]
	v_mov_b64_e32 v[62:63], v[30:31]
	v_mov_b64_e32 v[60:61], v[28:29]
	v_mov_b64_e32 v[58:59], v[26:27]
	v_mov_b64_e32 v[56:57], v[24:25]
	v_mov_b64_e32 v[54:55], v[22:23]
	v_mov_b64_e32 v[52:53], v[20:21]
	v_mov_b64_e32 v[50:51], v[18:19]
	v_mov_b64_e32 v[46:47], v[14:15]
	v_mov_b64_e32 v[44:45], v[12:13]
	v_mov_b64_e32 v[42:43], v[10:11]
	v_mov_b64_e32 v[40:41], v[8:9]
	v_mov_b64_e32 v[38:39], v[6:7]
	v_mov_b64_e32 v[36:37], v[4:5]
	v_mov_b64_e32 v[34:35], v[2:3]
	s_waitcnt vmcnt(0)
	v_mov_b32_e32 v49, v66

; __device__ __forceinline__ void tr_load(const float* W, int N, int mat, int item, int lane, int nblk, float (&x)[32]) {
;     const int kb = item / nblk, nb = item % nblk, k0 = 64 * kb, n0 = 32 * nb;
;     const int sc = src_col(mat, n0 + (lane & 31));
; #pragma unroll
;     for (int i = 0; i < 32; ++i) { const int kk = 2 * i + (lane >> 5); x[i] = sc >= 0 ? W[(size_t)(k0 + kk) * N + sc] : 0.f; }
; }
.LBB0_86:
	s_waitcnt vmcnt(1)
	v_or_b32_e32 v2, 32, v1
	s_mov_b32 s8, 0xd600
	s_waitcnt vmcnt(0)
	v_mad_i64_i32 v[2:3], s[6:7], v2, s8, v[100:101]
	v_or_b32_e32 v4, 34, v1
	v_mad_i64_i32 v[4:5], s[6:7], v4, s8, v[100:101]
	global_load_dword v50, v[2:3], off nt
	global_load_dword v66, v[4:5], off nt
	s_waitcnt vmcnt(1)
	v_mov_b64_e32 v[2:3], v[34:35]
	v_mov_b64_e32 v[18:19], v[50:51]
	v_mov_b64_e32 v[4:5], v[36:37]
	v_mov_b64_e32 v[6:7], v[38:39]
	v_mov_b64_e32 v[8:9], v[40:41]
	v_mov_b64_e32 v[10:11], v[42:43]
	v_mov_b64_e32 v[12:13], v[44:45]
	v_mov_b64_e32 v[14:15], v[46:47]
	v_mov_b64_e32 v[16:17], v[48:49]
	v_mov_b64_e32 v[20:21], v[52:53]
	v_mov_b64_e32 v[22:23], v[54:55]
	v_mov_b64_e32 v[24:25], v[56:57]
	v_mov_b64_e32 v[26:27], v[58:59]
	v_mov_b64_e32 v[28:29], v[60:61]
	v_mov_b64_e32 v[30:31], v[62:63]
	v_mov_b64_e32 v[32:33], v[64:65]
	s_waitcnt vmcnt(0)
	v_mov_b32_e32 v19, v66

; __device__ __forceinline__ void tr_load(const float* W, int N, int mat, int item, int lane, int nblk, float (&x)[32]) {
;     const int kb = item / nblk, nb = item % nblk, k0 = 64 * kb, n0 = 32 * nb;
;     const int sc = src_col(mat, n0 + (lane & 31));
; #pragma unroll
;     for (int i = 0; i < 32; ++i) { const int kk = 2 * i + (lane >> 5); x[i] = sc >= 0 ? W[(size_t)(k0 + kk) * N + sc] : 0.f; }
; }
.LBB0_90:
	s_waitcnt vmcnt(13)
	v_or_b32_e32 v20, 36, v1
	s_mov_b32 s8, 0xd600
	v_mad_i64_i32 v[34:35], s[6:7], v20, s8, v[100:101]
	v_or_b32_e32 v20, 38, v1
	v_mad_i64_i32 v[36:37], s[6:7], v20, s8, v[100:101]
	global_load_dword v20, v[34:35], off nt
	global_load_dword v66, v[36:37], off nt
	s_waitcnt vmcnt(1)
	v_mov_b64_e32 v[64:65], v[32:33]
	v_mov_b64_e32 v[52:53], v[20:21]
	v_mov_b64_e32 v[62:63], v[30:31]
	v_mov_b64_e32 v[60:61], v[28:29]
	v_mov_b64_e32 v[58:59], v[26:27]
	v_mov_b64_e32 v[56:57], v[24:25]
	v_mov_b64_e32 v[54:55], v[22:23]
	v_mov_b64_e32 v[50:51], v[18:19]
	v_mov_b64_e32 v[48:49], v[16:17]
	v_mov_b64_e32 v[46:47], v[14:15]
	v_mov_b64_e32 v[44:45], v[12:13]
	v_mov_b64_e32 v[42:43], v[10:11]
	v_mov_b64_e32 v[40:41], v[8:9]
	v_mov_b64_e32 v[38:39], v[6:7]
	v_mov_b64_e32 v[36:37], v[4:5]
	v_mov_b64_e32 v[34:35], v[2:3]
	s_waitcnt vmcnt(0)
	v_mov_b32_e32 v53, v66

; __device__ __forceinline__ void tr_load(const float* W, int N, int mat, int item, int lane, int nblk, float (&x)[32]) {
;     const int kb = item / nblk, nb = item % nblk, k0 = 64 * kb, n0 = 32 * nb;
;     const int sc = src_col(mat, n0 + (lane & 31));
; #pragma unroll
;     for (int i = 0; i < 32; ++i) { const int kk = 2 * i + (lane >> 5); x[i] = sc >= 0 ? W[(size_t)(k0 + kk) * N + sc] : 0.f; }
; }
.LBB0_94:
	s_waitcnt vmcnt(1)
	v_or_b32_e32 v2, 40, v1
	s_mov_b32 s8, 0xd600
	s_waitcnt vmcnt(0)
	v_mad_i64_i32 v[2:3], s[6:7], v2, s8, v[100:101]
	v_or_b32_e32 v4, 42, v1
	v_mad_i64_i32 v[4:5], s[6:7], v4, s8, v[100:101]
	global_load_dword v54, v[2:3], off nt
	global_load_dword v66, v[4:5], off nt
	s_waitcnt vmcnt(1)
	v_mov_b64_e32 v[2:3], v[34:35]
	v_mov_b64_e32 v[22:23], v[54:55]
	v_mov_b64_e32 v[4:5], v[36:37]
	v_mov_b64_e32 v[6:7], v[38:39]
	v_mov_b64_e32 v[8:9], v[40:41]
	v_mov_b64_e32 v[10:11], v[42:43]
	v_mov_b64_e32 v[12:13], v[44:45]
	v_mov_b64_e32 v[14:15], v[46:47]
	v_mov_b64_e32 v[16:17], v[48:49]
	v_mov_b64_e32 v[18:19], v[50:51]
	v_mov_b64_e32 v[20:21], v[52:53]
	v_mov_b64_e32 v[24:25], v[56:57]
	v_mov_b64_e32 v[26:27], v[58:59]
	v_mov_b64_e32 v[28:29], v[60:61]
	v_mov_b64_e32 v[30:31], v[62:63]
	v_mov_b64_e32 v[32:33], v[64:65]
	s_waitcnt vmcnt(0)
	v_mov_b32_e32 v23, v66

; __device__ __forceinline__ void tr_load(const float* W, int N, int mat, int item, int lane, int nblk, float (&x)[32]) {
;     const int kb = item / nblk, nb = item % nblk, k0 = 64 * kb, n0 = 32 * nb;
;     const int sc = src_col(mat, n0 + (lane & 31));
; #pragma unroll
;     for (int i = 0; i < 32; ++i) { const int kk = 2 * i + (lane >> 5); x[i] = sc >= 0 ? W[(size_t)(k0 + kk) * N + sc] : 0.f; }
; }
.LBB0_98:
	s_waitcnt vmcnt(9)
	v_or_b32_e32 v24, 44, v1
	s_mov_b32 s8, 0xd600
	v_mad_i64_i32 v[34:35], s[6:7], v24, s8, v[100:101]
	v_or_b32_e32 v24, 46, v1
	v_mad_i64_i32 v[36:37], s[6:7], v24, s8, v[100:101]
	global_load_dword v24, v[34:35], off nt
	global_load_dword v66, v[36:37], off nt
	s_waitcnt vmcnt(1)
	v_mov_b64_e32 v[64:65], v[32:33]
	v_mov_b64_e32 v[56:57], v[24:25]
	v_mov_b64_e32 v[62:63], v[30:31]
	v_mov_b64_e32 v[60:61], v[28:29]
	v_mov_b64_e32 v[58:59], v[26:27]
	v_mov_b64_e32 v[54:55], v[22:23]
	v_mov_b64_e32 v[52:53], v[20:21]
	v_mov_b64_e32 v[50:51], v[18:19]
	v_mov_b64_e32 v[48:49], v[16:17]
	v_mov_b64_e32 v[46:47], v[14:15]
	v_mov_b64_e32 v[44:45], v[12:13]
	v_mov_b64_e32 v[42:43], v[10:11]
	v_mov_b64_e32 v[40:41], v[8:9]
	v_mov_b64_e32 v[38:39], v[6:7]
	v_mov_b64_e32 v[36:37], v[4:5]
	v_mov_b64_e32 v[34:35], v[2:3]
	s_waitcnt vmcnt(0)
	v_mov_b32_e32 v57, v66

; __device__ __forceinline__ void tr_load(const float* W, int N, int mat, int item, int lane, int nblk, float (&x)[32]) {
;     const int kb = item / nblk, nb = item % nblk, k0 = 64 * kb, n0 = 32 * nb;
;     const int sc = src_col(mat, n0 + (lane & 31));
; #pragma unroll
;     for (int i = 0; i < 32; ++i) { const int kk = 2 * i + (lane >> 5); x[i] = sc >= 0 ? W[(size_t)(k0 + kk) * N + sc] : 0.f; }
; }
.LBB0_102:
	s_waitcnt vmcnt(1)
	v_or_b32_e32 v2, 48, v1
	s_mov_b32 s8, 0xd600
	s_waitcnt vmcnt(0)
	v_mad_i64_i32 v[2:3], s[6:7], v2, s8, v[100:101]
	v_or_b32_e32 v4, 50, v1
	v_mad_i64_i32 v[4:5], s[6:7], v4, s8, v[100:101]
	global_load_dword v58, v[2:3], off nt
	s_nop 0
	global_load_dword v2, v[4:5], off nt
	s_waitcnt vmcnt(1)
	v_mov_b64_e32 v[96:97], v[64:65]
	v_mov_b64_e32 v[90:91], v[58:59]
	v_mov_b64_e32 v[94:95], v[62:63]
	v_mov_b64_e32 v[92:93], v[60:61]
	v_mov_b64_e32 v[88:89], v[56:57]
	v_mov_b64_e32 v[86:87], v[54:55]
	v_mov_b64_e32 v[84:85], v[52:53]
	v_mov_b64_e32 v[82:83], v[50:51]
	v_mov_b64_e32 v[80:81], v[48:49]
	v_mov_b64_e32 v[78:79], v[46:47]
	v_mov_b64_e32 v[76:77], v[44:45]
	v_mov_b64_e32 v[74:75], v[42:43]
	v_mov_b64_e32 v[72:73], v[40:41]
	v_mov_b64_e32 v[70:71], v[38:39]
	v_mov_b64_e32 v[68:69], v[36:37]
	v_mov_b64_e32 v[66:67], v[34:35]
	s_waitcnt vmcnt(0)
	v_mov_b32_e32 v91, v2

; __device__ __forceinline__ void tr_load(const float* W, int N, int mat, int item, int lane, int nblk, float (&x)[32]) {
;     const int kb = item / nblk, nb = item % nblk, k0 = 64 * kb, n0 = 32 * nb;
;     const int sc = src_col(mat, n0 + (lane & 31));
; #pragma unroll
;     for (int i = 0; i < 32; ++i) { const int kk = 2 * i + (lane >> 5); x[i] = sc >= 0 ? W[(size_t)(k0 + kk) * N + sc] : 0.f; }
; }
.LBB0_108:
.LBB0_109:
	s_or_saveexec_b64 s[0:1], s[0:1]
	s_waitcnt vmcnt(1)
	v_mov_b32_e32 v32, 0
	s_waitcnt vmcnt(0)
	v_mov_b32_e32 v33, 0
	s_xor_b64 exec, exec, s[0:1]
	s_cbranch_execz .LBB0_111
	v_or_b32_e32 v32, 60, v1
	s_mov_b32 s8, 0xd600
	v_mad_i64_i32 v[32:33], s[6:7], v32, s8, v[100:101]
	v_or_b32_e32 v1, 62, v1
	v_mad_i64_i32 v[34:35], s[6:7], v1, s8, v[100:101]
	global_load_dword v32, v[32:33], off nt
	s_nop 0
	global_load_dword v33, v[34:35], off nt

; __device__ __forceinline__ void tr_load(const float* W, int N, int mat, int item, int lane, int nblk, float (&x)[32]) {
;     const int kb = item / nblk, nb = item % nblk, k0 = 64 * kb, n0 = 32 * nb;
;     const int sc = src_col(mat, n0 + (lane & 31));
; #pragma unroll
;     for (int i = 0; i < 32; ++i) { const int kk = 2 * i + (lane >> 5); x[i] = sc >= 0 ? W[(size_t)(k0 + kk) * N + sc] : 0.f; }
; }
.LBB0_131:
	v_lshl_add_u64 v[42:43], v[34:35], 0, v[66:67]
	v_lshl_add_u64 v[34:35], v[42:43], 0, s[6:7]
	v_lshl_add_u64 v[36:37], v[42:43], 0, s[8:9]
	v_lshl_add_u64 v[38:39], v[42:43], 0, s[14:15]
	v_lshl_add_u64 v[40:41], v[42:43], 0, s[16:17]
	v_lshl_add_u64 v[44:45], v[42:43], 0, s[18:19]
	v_lshl_add_u64 v[46:47], v[42:43], 0, s[20:21]
	v_lshl_add_u64 v[48:49], v[42:43], 0, s[22:23]
	v_lshl_add_u64 v[50:51], v[42:43], 0, s[24:25]
	v_lshl_add_u64 v[52:53], v[42:43], 0, s[34:35]
	v_lshl_add_u64 v[54:55], v[42:43], 0, s[54:55]
	v_lshl_add_u64 v[56:57], v[42:43], 0, s[58:59]
	v_lshl_add_u64 v[58:59], v[42:43], 0, s[60:61]
	v_lshl_add_u64 v[60:61], v[42:43], 0, s[62:63]
	v_lshl_add_u64 v[62:63], v[42:43], 0, s[84:85]
	v_lshl_add_u64 v[64:65], v[42:43], 0, s[86:87]
	v_lshl_add_u64 v[76:77], v[42:43], 0, s[90:91]
	v_lshl_add_u64 v[88:89], v[42:43], 0, s[96:97]
	v_lshl_add_u64 v[90:91], v[42:43], 0, vcc
	v_lshl_add_u64 v[92:93], v[42:43], 0, s[26:27]
	v_lshl_add_u64 v[94:95], v[42:43], 0, s[36:37]
	v_lshl_add_u64 v[96:97], v[42:43], 0, s[38:39]
	v_lshl_add_u64 v[100:101], v[42:43], 0, s[40:41]
	v_lshl_add_u64 v[102:103], v[42:43], 0, s[42:43]
	v_lshl_add_u64 v[104:105], v[42:43], 0, s[44:45]
	v_lshl_add_u64 v[106:107], v[42:43], 0, s[46:47]
	v_lshl_add_u64 v[108:109], v[42:43], 0, s[48:49]
	v_lshl_add_u64 v[110:111], v[42:43], 0, s[50:51]
	v_lshl_add_u64 v[112:113], v[42:43], 0, s[10:11]
	v_lshl_add_u64 v[114:115], v[42:43], 0, s[68:69]
	global_load_dword v35, v[34:35], off nt
	s_nop 0
	global_load_dword v36, v[36:37], off nt
	s_nop 0
	global_load_dword v37, v[38:39], off nt
	s_nop 0
	global_load_dword v38, v[40:41], off nt
	global_load_dword v39, v[44:45], off nt
	s_nop 0
	global_load_dword v40, v[46:47], off nt
	global_load_dword v41, v[48:49], off nt
	global_load_dword v34, v[42:43], off nt
	v_lshl_add_u64 v[116:117], v[42:43], 0, s[88:89]
	v_lshl_add_u64 v[118:119], v[42:43], 0, s[94:95]
	global_load_dword v42, v[50:51], off nt
	global_load_dword v43, v[52:53], off nt
	global_load_dword v44, v[54:55], off nt
	global_load_dword v45, v[56:57], off nt
	global_load_dword v46, v[58:59], off nt
	global_load_dword v47, v[60:61], off nt
	global_load_dword v48, v[62:63], off nt
	global_load_dword v49, v[64:65], off nt
	global_load_dword v50, v[76:77], off nt
	global_load_dword v51, v[88:89], off nt
	global_load_dword v52, v[90:91], off nt
	global_load_dword v53, v[92:93], off nt
	global_load_dword v54, v[94:95], off nt
	global_load_dword v55, v[96:97], off nt
	global_load_dword v56, v[100:101], off nt
	global_load_dword v57, v[102:103], off nt
	global_load_dword v58, v[104:105], off nt
	global_load_dword v59, v[106:107], off nt
	global_load_dword v60, v[108:109], off nt
	global_load_dword v61, v[110:111], off nt
	global_load_dword v62, v[112:113], off nt
	global_load_dword v63, v[114:115], off nt
	global_load_dword v64, v[116:117], off nt
	global_load_dword v65, v[118:119], off nt
	v_readlane_b32 s84, v254, 56
	v_readlane_b32 s96, v254, 52
	v_readlane_b32 s30, v254, 54
	v_readlane_b32 s88, v254, 58
	s_mov_b64 s[6:7], 0
	v_readlane_b32 s85, v254, 57
	s_mov_b32 s48, s84
	v_readlane_b32 s97, v254, 53
	v_readlane_b32 s31, v254, 55
	v_readlane_b32 s89, v254, 59
; __device__ __forceinline__ void tr_load(const float* W, int N, int mat, int item, int lane, int nblk, float (&x)[32]) {
;     const int kb = item / nblk, nb = item % nblk, k0 = 64 * kb, n0 = 32 * nb;
;     const int sc = src_col(mat, n0 + (lane & 31));
; #pragma unroll
;     for (int i = 0; i < 32; ++i) { const int kk = 2 * i + (lane >> 5); x[i] = sc >= 0 ? W[(size_t)(k0 + kk) * N + sc] : 0.f; }
; }
.LBB0_132:
	s_and_b64 vcc, exec, s[6:7]
	s_cbranch_vccz .LBB0_134
	s_add_i32 s6, s73, s72
	s_add_i32 s0, s76, 0x9400
	s_add_i32 s6, s6, 0x38000
	s_lshr_b32 s0, s0, 1
	s_and_b32 s6, s6, 0xfe0
	s_and_b32 s0, s0, 0x7fc0
	s_waitcnt vmcnt(24)
	v_or_b32_e32 v34, s6, v1
	s_mov_b64 s[6:7], s[92:93]
	v_readlane_b32 s80, v254, 20
	v_or_b32_e32 v36, s0, v78
	v_lshlrev_b32_e32 v66, 2, v34
	v_readlane_b32 s81, v254, 21
	s_mov_b32 s0, 0x38000
	v_readlane_b32 s88, v254, 28
	v_lshl_add_u64 v[34:35], s[80:81], 0, v[66:67]
	v_lshlrev_b32_e32 v66, 14, v36
	s_waitcnt vmcnt(6)
	v_lshl_add_u64 v[58:59], v[34:35], 0, v[66:67]
	v_add_co_u32_e32 v36, vcc, 0x8000, v58
	v_readlane_b32 s89, v254, 29
	s_nop 0
	v_addc_co_u32_e32 v37, vcc, 0, v59, vcc
	v_add_co_u32_e32 v38, vcc, 0x10000, v58
	v_readlane_b32 s92, v254, 32
	s_nop 0
	v_addc_co_u32_e32 v39, vcc, 0, v59, vcc
	v_add_co_u32_e32 v40, vcc, 0x18000, v58
	v_readlane_b32 s93, v254, 33
	s_nop 0
	v_addc_co_u32_e32 v41, vcc, 0, v59, vcc
	v_add_co_u32_e32 v42, vcc, 0x20000, v58
	v_readlane_b32 s88, v254, 58
	s_nop 0
	v_addc_co_u32_e32 v43, vcc, 0, v59, vcc
	v_add_co_u32_e32 v44, vcc, 0x28000, v58
	v_readlane_b32 s89, v254, 59
	s_nop 0
	v_addc_co_u32_e32 v45, vcc, 0, v59, vcc
	v_add_co_u32_e32 v46, vcc, 0x30000, v58
	s_mov_b64 s[92:93], s[6:7]
	s_nop 0
	v_addc_co_u32_e32 v47, vcc, 0, v59, vcc
	v_add_co_u32_e32 v48, vcc, s0, v58
	v_readlane_b32 s82, v254, 22
	s_nop 0
	v_addc_co_u32_e32 v49, vcc, 0, v59, vcc
	global_load_dword v34, v[58:59], off nt
	global_load_dword v35, v[36:37], off nt
	s_nop 0
	global_load_dword v36, v[38:39], off nt
	global_load_dword v37, v[40:41], off nt
	s_nop 0
	global_load_dword v38, v[42:43], off nt
	global_load_dword v39, v[44:45], off nt
	global_load_dword v40, v[46:47], off nt
	global_load_dword v41, v[48:49], off nt
	v_add_co_u32_e32 v42, vcc, 0x40000, v58
	v_readlane_b32 s83, v254, 23
	s_nop 0
	v_addc_co_u32_e32 v43, vcc, 0, v59, vcc
	v_add_co_u32_e32 v44, vcc, 0x48000, v58
	v_readlane_b32 s84, v254, 24
	s_nop 0
	v_addc_co_u32_e32 v45, vcc, 0, v59, vcc
	v_add_co_u32_e32 v46, vcc, 0x50000, v58
	v_readlane_b32 s85, v254, 25
	s_nop 0
	v_addc_co_u32_e32 v47, vcc, 0, v59, vcc
	v_add_co_u32_e32 v48, vcc, 0x58000, v58
	v_readlane_b32 s86, v254, 26
	s_nop 0
	v_addc_co_u32_e32 v49, vcc, 0, v59, vcc
	v_add_co_u32_e32 v50, vcc, 0x60000, v58
	v_readlane_b32 s87, v254, 27
	s_nop 0
	v_addc_co_u32_e32 v51, vcc, 0, v59, vcc
	v_add_co_u32_e32 v52, vcc, 0x68000, v58
	v_readlane_b32 s90, v254, 30
	s_nop 0
	v_addc_co_u32_e32 v53, vcc, 0, v59, vcc
	v_add_co_u32_e32 v54, vcc, 0x70000, v58
	v_readlane_b32 s91, v254, 31
	s_nop 0
	v_addc_co_u32_e32 v55, vcc, 0, v59, vcc
	v_add_co_u32_e32 v56, vcc, 0x78000, v58
	v_readlane_b32 s94, v254, 34
	s_nop 0
	v_addc_co_u32_e32 v57, vcc, 0, v59, vcc
	global_load_dword v42, v[42:43], off nt
	s_nop 0
	global_load_dword v43, v[44:45], off nt
	s_nop 0
	global_load_dword v44, v[46:47], off nt
	global_load_dword v45, v[48:49], off nt
	s_nop 0
	global_load_dword v46, v[50:51], off nt
	global_load_dword v47, v[52:53], off nt
	global_load_dword v48, v[54:55], off nt
	global_load_dword v49, v[56:57], off nt
	v_add_co_u32_e32 v50, vcc, 0x80000, v58
	v_readlane_b32 s95, v254, 35
	s_nop 0
	v_addc_co_u32_e32 v51, vcc, 0, v59, vcc
	v_add_co_u32_e32 v52, vcc, 0x88000, v58
	s_nop 1
	v_addc_co_u32_e32 v53, vcc, 0, v59, vcc
	v_add_co_u32_e32 v54, vcc, 0x90000, v58
	s_nop 1
	v_addc_co_u32_e32 v55, vcc, 0, v59, vcc
	v_add_co_u32_e32 v56, vcc, 0x98000, v58
	s_nop 1
	v_addc_co_u32_e32 v57, vcc, 0, v59, vcc
	s_waitcnt vmcnt(21)
	v_add_co_u32_e32 v60, vcc, 0xa0000, v58
	s_waitcnt vmcnt(20)
	s_nop 0
	v_addc_co_u32_e32 v61, vcc, 0, v59, vcc
	s_waitcnt vmcnt(19)
	v_add_co_u32_e32 v62, vcc, 0xa8000, v58
	s_waitcnt vmcnt(18)
	s_nop 0
	v_addc_co_u32_e32 v63, vcc, 0, v59, vcc
	s_waitcnt vmcnt(17)
	v_add_co_u32_e32 v64, vcc, 0xb0000, v58
	s_waitcnt vmcnt(16)
	s_nop 0
	v_addc_co_u32_e32 v65, vcc, 0, v59, vcc
	v_add_co_u32_e32 v76, vcc, 0xb8000, v58
	s_nop 1
	v_addc_co_u32_e32 v77, vcc, 0, v59, vcc
	global_load_dword v50, v[50:51], off nt
	s_nop 0
	global_load_dword v51, v[52:53], off nt
	s_nop 0
	global_load_dword v52, v[54:55], off nt
	global_load_dword v53, v[56:57], off nt
	s_nop 0
	global_load_dword v54, v[60:61], off nt
	global_load_dword v55, v[62:63], off nt
	global_load_dword v56, v[64:65], off nt
	global_load_dword v57, v[76:77], off nt
	v_add_co_u32_e32 v60, vcc, 0xc0000, v58
	s_nop 1
	v_addc_co_u32_e32 v61, vcc, 0, v59, vcc
	v_add_co_u32_e32 v62, vcc, 0xc8000, v58
	s_nop 1
	v_addc_co_u32_e32 v63, vcc, 0, v59, vcc
	v_add_co_u32_e32 v64, vcc, 0xd0000, v58
	s_nop 1
	v_addc_co_u32_e32 v65, vcc, 0, v59, vcc
	v_add_co_u32_e32 v76, vcc, 0xd8000, v58
	s_nop 1
	v_addc_co_u32_e32 v77, vcc, 0, v59, vcc
	v_add_co_u32_e32 v88, vcc, 0xe0000, v58
	s_nop 1
	v_addc_co_u32_e32 v89, vcc, 0, v59, vcc
	v_add_co_u32_e32 v90, vcc, 0xe8000, v58
	s_nop 1
	v_addc_co_u32_e32 v91, vcc, 0, v59, vcc
	v_add_co_u32_e32 v92, vcc, 0xf0000, v58
	s_nop 1
	v_addc_co_u32_e32 v93, vcc, 0, v59, vcc
	v_add_co_u32_e32 v94, vcc, 0xf8000, v58
	s_nop 1
	v_addc_co_u32_e32 v95, vcc, 0, v59, vcc
	global_load_dword v58, v[60:61], off nt
	global_load_dword v59, v[62:63], off nt
	s_nop 0
	global_load_dword v60, v[64:65], off nt
	global_load_dword v61, v[76:77], off nt
	global_load_dword v62, v[88:89], off nt
	global_load_dword v63, v[90:91], off nt
	s_nop 0
	global_load_dword v64, v[92:93], off nt
	global_load_dword v65, v[94:95], off nt

; __device__ __forceinline__ void tr_load(const float* W, int N, int mat, int item, int lane, int nblk, float (&x)[32]) {
;     const int kb = item / nblk, nb = item % nblk, k0 = 64 * kb, n0 = 32 * nb;
;     const int sc = src_col(mat, n0 + (lane & 31));
; #pragma unroll
;     for (int i = 0; i < 32; ++i) { const int kk = 2 * i + (lane >> 5); x[i] = sc >= 0 ? W[(size_t)(k0 + kk) * N + sc] : 0.f; }
; }
.LBB0_144:
	s_or_b64 exec, exec, s[6:7]
	v_cmp_lt_i32_e32 vcc, -1, v66
	v_lshl_or_b32 v87, s0, 6, v78
	v_lshl_add_u64 v[76:77], v[66:67], 2, s[66:67]
	v_mov_b32_e32 v36, 0
	v_mov_b32_e32 v34, 0
	v_mov_b32_e32 v35, 0
	s_and_saveexec_b64 s[6:7], vcc
	s_cbranch_execz .LBB0_146
	v_mad_i64_i32 v[34:35], s[8:9], v87, s75, v[76:77]
	v_or_b32_e32 v37, 2, v87
	v_mad_i64_i32 v[38:39], s[8:9], v37, s75, v[76:77]
	global_load_dword v34, v[34:35], off nt
	s_nop 0
	global_load_dword v35, v[38:39], off nt
.LBB0_146:
	s_or_b64 exec, exec, s[6:7]
	v_mov_b32_e32 v37, 0
	s_and_saveexec_b64 s[6:7], vcc
	s_cbranch_execz .LBB0_148
	v_or_b32_e32 v36, 4, v87
	v_mad_i64_i32 v[36:37], s[8:9], v36, s75, v[76:77]
	v_or_b32_e32 v38, 6, v87
	v_mad_i64_i32 v[38:39], s[8:9], v38, s75, v[76:77]
	global_load_dword v36, v[36:37], off nt
	s_nop 0
	global_load_dword v37, v[38:39], off nt
.LBB0_148:
	s_or_b64 exec, exec, s[6:7]
	v_mov_b32_e32 v40, 0
	v_mov_b32_e32 v38, 0
	v_mov_b32_e32 v39, 0
	s_and_saveexec_b64 s[6:7], vcc
	s_cbranch_execz .LBB0_150
	v_or_b32_e32 v38, 8, v87
	v_mad_i64_i32 v[38:39], s[8:9], v38, s75, v[76:77]
	v_or_b32_e32 v41, 10, v87
	s_waitcnt vmcnt(22)
	v_mad_i64_i32 v[42:43], s[8:9], v41, s75, v[76:77]
	global_load_dword v38, v[38:39], off nt
	s_nop 0
	global_load_dword v39, v[42:43], off nt
.LBB0_150:
	s_or_b64 exec, exec, s[6:7]
	v_mov_b32_e32 v41, 0
	s_and_saveexec_b64 s[6:7], vcc
	s_cbranch_execz .LBB0_152
	v_or_b32_e32 v40, 12, v87
	v_mad_i64_i32 v[40:41], s[8:9], v40, s75, v[76:77]
	s_waitcnt vmcnt(23)
	v_or_b32_e32 v42, 14, v87
	s_waitcnt vmcnt(22)
	v_mad_i64_i32 v[42:43], s[8:9], v42, s75, v[76:77]
	global_load_dword v40, v[40:41], off nt
	s_nop 0
	global_load_dword v41, v[42:43], off nt
.LBB0_152:
	s_or_b64 exec, exec, s[6:7]
	s_waitcnt vmcnt(21)
	v_mov_b32_e32 v44, 0
	v_mov_b32_e32 v42, 0
	v_mov_b32_e32 v43, 0
	s_and_saveexec_b64 s[6:7], vcc
	s_cbranch_execz .LBB0_154
	v_or_b32_e32 v42, 16, v87
	v_mad_i64_i32 v[42:43], s[8:9], v42, s75, v[76:77]
	s_waitcnt vmcnt(20)
	v_or_b32_e32 v45, 18, v87
	s_waitcnt vmcnt(18)
	v_mad_i64_i32 v[46:47], s[8:9], v45, s75, v[76:77]
	global_load_dword v42, v[42:43], off nt
	s_nop 0
	global_load_dword v43, v[46:47], off nt
.LBB0_154:
	s_or_b64 exec, exec, s[6:7]
	s_waitcnt vmcnt(20)
	v_mov_b32_e32 v45, 0
	s_and_saveexec_b64 s[6:7], vcc
	s_cbranch_execz .LBB0_156
	v_or_b32_e32 v44, 20, v87
	v_mad_i64_i32 v[44:45], s[8:9], v44, s75, v[76:77]
	s_waitcnt vmcnt(19)
	v_or_b32_e32 v46, 22, v87
	s_waitcnt vmcnt(18)
	v_mad_i64_i32 v[46:47], s[8:9], v46, s75, v[76:77]
	global_load_dword v44, v[44:45], off nt
	s_nop 0
	global_load_dword v45, v[46:47], off nt
.LBB0_156:
	s_or_b64 exec, exec, s[6:7]
	s_waitcnt vmcnt(17)
	v_mov_b32_e32 v48, 0
	v_mov_b32_e32 v46, 0
	v_mov_b32_e32 v47, 0
	s_and_saveexec_b64 s[6:7], vcc
	s_cbranch_execz .LBB0_158
	v_or_b32_e32 v46, 24, v87
	v_mad_i64_i32 v[46:47], s[8:9], v46, s75, v[76:77]
	s_waitcnt vmcnt(16)
	v_or_b32_e32 v49, 26, v87
	s_waitcnt vmcnt(14)
	v_mad_i64_i32 v[50:51], s[8:9], v49, s75, v[76:77]
	global_load_dword v46, v[46:47], off nt
	s_nop 0
	global_load_dword v47, v[50:51], off nt
.LBB0_158:
	s_or_b64 exec, exec, s[6:7]
	s_waitcnt vmcnt(16)
	v_mov_b32_e32 v49, 0
	s_and_saveexec_b64 s[6:7], vcc
	s_cbranch_execz .LBB0_160
	v_or_b32_e32 v48, 28, v87
	v_mad_i64_i32 v[48:49], s[8:9], v48, s75, v[76:77]
	s_waitcnt vmcnt(15)
	v_or_b32_e32 v50, 30, v87
	s_waitcnt vmcnt(14)
	v_mad_i64_i32 v[50:51], s[8:9], v50, s75, v[76:77]
	global_load_dword v48, v[48:49], off nt
	s_nop 0
	global_load_dword v49, v[50:51], off nt
; __device__ __forceinline__ void tr_load(const float* W, int N, int mat, int item, int lane, int nblk, float (&x)[32]) {
;     const int kb = item / nblk, nb = item % nblk, k0 = 64 * kb, n0 = 32 * nb;
;     const int sc = src_col(mat, n0 + (lane & 31));
; #pragma unroll
;     for (int i = 0; i < 32; ++i) { const int kk = 2 * i + (lane >> 5); x[i] = sc >= 0 ? W[(size_t)(k0 + kk) * N + sc] : 0.f; }
; }
.LBB0_160:
	s_or_b64 exec, exec, s[6:7]
	s_waitcnt vmcnt(13)
	v_mov_b32_e32 v52, 0
	v_mov_b32_e32 v50, 0
	v_mov_b32_e32 v51, 0
	s_and_saveexec_b64 s[6:7], vcc
	s_cbranch_execz .LBB0_162
	v_or_b32_e32 v50, 32, v87
	v_mad_i64_i32 v[50:51], s[8:9], v50, s75, v[76:77]
	s_waitcnt vmcnt(12)
	v_or_b32_e32 v53, 34, v87
	s_waitcnt vmcnt(10)
	v_mad_i64_i32 v[54:55], s[8:9], v53, s75, v[76:77]
	global_load_dword v50, v[50:51], off nt
	s_nop 0
	global_load_dword v51, v[54:55], off nt
.LBB0_162:
	s_or_b64 exec, exec, s[6:7]
	s_waitcnt vmcnt(12)
	v_mov_b32_e32 v53, 0
	s_and_saveexec_b64 s[6:7], vcc
	s_cbranch_execz .LBB0_164
	v_or_b32_e32 v52, 36, v87
	v_mad_i64_i32 v[52:53], s[8:9], v52, s75, v[76:77]
	s_waitcnt vmcnt(11)
	v_or_b32_e32 v54, 38, v87
	s_waitcnt vmcnt(10)
	v_mad_i64_i32 v[54:55], s[8:9], v54, s75, v[76:77]
	global_load_dword v52, v[52:53], off nt
	s_nop 0
	global_load_dword v53, v[54:55], off nt
.LBB0_164:
	s_or_b64 exec, exec, s[6:7]
	s_waitcnt vmcnt(9)
	v_mov_b32_e32 v56, 0
	v_mov_b32_e32 v54, 0
	v_mov_b32_e32 v55, 0
	s_and_saveexec_b64 s[6:7], vcc
	s_cbranch_execz .LBB0_166
	v_or_b32_e32 v54, 40, v87
	v_mad_i64_i32 v[54:55], s[8:9], v54, s75, v[76:77]
	s_waitcnt vmcnt(8)
	v_or_b32_e32 v57, 42, v87
	s_waitcnt vmcnt(6)
	v_mad_i64_i32 v[58:59], s[8:9], v57, s75, v[76:77]
	global_load_dword v54, v[54:55], off nt
	s_nop 0
	global_load_dword v55, v[58:59], off nt
.LBB0_166:
	s_or_b64 exec, exec, s[6:7]
	s_waitcnt vmcnt(8)
	v_mov_b32_e32 v57, 0
	s_and_saveexec_b64 s[6:7], vcc
	s_cbranch_execz .LBB0_168
	v_or_b32_e32 v56, 44, v87
	v_mad_i64_i32 v[56:57], s[8:9], v56, s75, v[76:77]
	s_waitcnt vmcnt(7)
	v_or_b32_e32 v58, 46, v87
	s_waitcnt vmcnt(6)
	v_mad_i64_i32 v[58:59], s[8:9], v58, s75, v[76:77]
	global_load_dword v56, v[56:57], off nt
	s_nop 0
	global_load_dword v57, v[58:59], off nt
.LBB0_168:
	s_or_b64 exec, exec, s[6:7]
	s_waitcnt vmcnt(5)
	v_mov_b32_e32 v60, 0
	v_mov_b32_e32 v58, 0
	v_mov_b32_e32 v59, 0
	s_and_saveexec_b64 s[6:7], vcc
	s_cbranch_execz .LBB0_170
	v_or_b32_e32 v58, 48, v87
	v_mad_i64_i32 v[58:59], s[8:9], v58, s75, v[76:77]
	s_waitcnt vmcnt(4)
	v_or_b32_e32 v61, 50, v87
	s_waitcnt vmcnt(2)
	v_mad_i64_i32 v[62:63], s[8:9], v61, s75, v[76:77]
	global_load_dword v58, v[58:59], off nt
	s_nop 0
	global_load_dword v59, v[62:63], off nt
.LBB0_170:
	s_or_b64 exec, exec, s[6:7]
	s_waitcnt vmcnt(4)
	v_mov_b32_e32 v61, 0
	s_and_saveexec_b64 s[6:7], vcc
	s_cbranch_execz .LBB0_172
	v_or_b32_e32 v60, 52, v87
	v_mad_i64_i32 v[60:61], s[8:9], v60, s75, v[76:77]
	s_waitcnt vmcnt(3)
	v_or_b32_e32 v62, 54, v87
	s_waitcnt vmcnt(2)
	v_mad_i64_i32 v[62:63], s[8:9], v62, s75, v[76:77]
	global_load_dword v60, v[60:61], off nt
	s_nop 0
	global_load_dword v61, v[62:63], off nt
.LBB0_172:
	s_or_b64 exec, exec, s[6:7]
	s_waitcnt vmcnt(1)
	v_mov_b32_e32 v64, 0
	v_mov_b32_e32 v62, 0
	v_mov_b32_e32 v63, 0
	s_and_saveexec_b64 s[6:7], vcc
	s_cbranch_execz .LBB0_174
	v_or_b32_e32 v62, 56, v87
	v_mad_i64_i32 v[62:63], s[8:9], v62, s75, v[76:77]
	s_waitcnt vmcnt(0)
	v_or_b32_e32 v65, 58, v87
	v_mad_i64_i32 v[88:89], s[8:9], v65, s75, v[76:77]
	global_load_dword v62, v[62:63], off nt
	s_nop 0
	global_load_dword v63, v[88:89], off nt
.LBB0_174:
	s_or_b64 exec, exec, s[6:7]
	s_waitcnt vmcnt(0)
	v_mov_b32_e32 v65, 0
	s_and_saveexec_b64 s[6:7], vcc
	s_cbranch_execz .LBB0_176
	v_or_b32_e32 v64, 60, v87
	v_mad_i64_i32 v[64:65], s[8:9], v64, s75, v[76:77]
	v_or_b32_e32 v66, 62, v87
	v_mad_i64_i32 v[76:77], s[8:9], v66, s75, v[76:77]
	global_load_dword v64, v[64:65], off nt
	s_nop 0
	global_load_dword v65, v[76:77], off nt

; __device__ __forceinline__ unsigned f2bf(float f) { unsigned u = __builtin_bit_cast(unsigned, f); return (u + 0x7fffu + ((u >> 16) & 1u)) >> 16; }
; __device__ __forceinline__ void p0_phase(const Args& a, LAS unsigned char* lds) {
;     ...
;         for (size_t i = gt; i < (size_t)8192 * 128; i += GT) {
;             const int n = (int)(i >> 7), r = (int)(i & 127), kind = n >> 11, c = n & 2047, dir = kind & 1;
;             float v = 0.f;
;             if (r < 96) { const float* src = (kind < 2) ? a.in[I_W2] : a.in[I_A2]; v = src[((size_t)dir * 96 + r) * BW + c]; }
;             wl[i] = (bf16)f2bf(v);
;         }
.LBB0_192:
	v_and_b32_e32 v6, 0x60, v8
	v_cmp_ne_u64_e32 vcc, s[8:9], v[6:7]
	v_mov_b32_e32 v6, 0
	s_and_saveexec_b64 s[18:19], vcc
	s_cbranch_execz .LBB0_191
	v_readlane_b32 s72, v254, 20
	v_readlane_b32 s81, v254, 29
	v_readlane_b32 s85, v254, 33
	v_readlane_b32 s80, v254, 28
	v_readlane_b32 s84, v254, 32
	v_mov_b32_e32 v6, s85
	s_waitcnt vmcnt(22)
	v_mov_b32_e32 v11, s81
	v_cmp_gt_u64_e32 vcc, s[10:11], v[8:9]
	v_readlane_b32 s73, v254, 21
	v_readlane_b32 s74, v254, 22
	s_waitcnt vmcnt(20)
	v_cndmask_b32_e32 v13, v6, v11, vcc
	v_mov_b32_e32 v6, s84
	v_mov_b32_e32 v11, s80
	v_cndmask_b32_e32 v12, v6, v11, vcc
	v_and_b32_e32 v6, 0x40000, v8
	v_cmp_eq_u64_e32 vcc, 0, v[6:7]
	v_readlane_b32 s75, v254, 23
	v_readlane_b32 s76, v254, 24
	v_cndmask_b32_e64 v6, v10, 0, vcc
	v_add_lshl_u32 v6, v6, v1, 13
	v_lshl_add_u64 v[12:13], v[12:13], 0, v[6:7]
	v_lshrrev_b32_e32 v6, 5, v8
	v_and_b32_e32 v6, 0x1ffc, v6
	v_lshl_add_u64 v[12:13], v[12:13], 0, v[6:7]
	global_load_dword v6, v[12:13], off nt
	v_readlane_b32 s77, v254, 25
	v_readlane_b32 s78, v254, 26
	v_readlane_b32 s79, v254, 27
	v_readlane_b32 s82, v254, 30
	v_readlane_b32 s83, v254, 31
	v_readlane_b32 s86, v254, 34
	v_readlane_b32 s87, v254, 35
	s_branch .LBB0_191

; __device__ __forceinline__ unsigned f2bf(float f) { unsigned u = __builtin_bit_cast(unsigned, f); return (u + 0x7fffu + ((u >> 16) & 1u)) >> 16; }
; __device__ __forceinline__ void p0_phase(const Args& a, LAS unsigned char* lds) {
;     ...
;         for (size_t i = gt; i < (size_t)16 * 128 * 128; i += GT) wsb[i] = (bf16)f2bf(a.in[I_WS][i]);
.LBB0_196:
	global_load_dword v1, v[4:5], off nt
	v_lshl_add_u64 v[8:9], v[8:9], 0, s[16:17]
	v_cmp_lt_u64_e32 vcc, s[10:11], v[8:9]
	v_lshl_add_u64 v[4:5], v[4:5], 0, s[4:5]
	s_or_b64 s[8:9], vcc, s[8:9]
	s_waitcnt vmcnt(0)
	v_bfe_u32 v10, v1, 16, 1
	v_add3_u32 v1, v1, v10, s14
	global_store_short_d16_hi v[6:7], v1, off
	v_lshl_add_u64 v[6:7], v[6:7], 0, s[6:7]
	s_andn2_b64 exec, exec, s[8:9]
	s_cbranch_execnz .LBB0_196

; __device__ __forceinline__ void tr_load(const float* W, int N, int mat, int item, int lane, int nblk, float (&x)[32]) {
;     const int kb = item / nblk, nb = item % nblk, k0 = 64 * kb, n0 = 32 * nb;
;     const int sc = src_col(mat, n0 + (lane & 31));
; #pragma unroll
;     for (int i = 0; i < 32; ++i) { const int kk = 2 * i + (lane >> 5); x[i] = sc >= 0 ? W[(size_t)(k0 + kk) * N + sc] : 0.f; }
; }
.LBB0_223:
	s_waitcnt vmcnt(1)
	v_or_b32_e32 v2, 52, v1
	s_mov_b32 s8, 0xd600
	s_waitcnt vmcnt(0)
	v_mad_i64_i32 v[2:3], s[6:7], v2, s8, v[100:101]
	v_or_b32_e32 v4, 54, v1
	v_mad_i64_i32 v[4:5], s[6:7], v4, s8, v[100:101]
	global_load_dword v92, v[2:3], off nt
	global_load_dword v34, v[4:5], off nt
	s_waitcnt vmcnt(1)
	v_mov_b64_e32 v[2:3], v[66:67]
	v_mov_b64_e32 v[28:29], v[92:93]
	v_mov_b64_e32 v[4:5], v[68:69]
	v_mov_b64_e32 v[6:7], v[70:71]
	v_mov_b64_e32 v[8:9], v[72:73]
	v_mov_b64_e32 v[10:11], v[74:75]
	v_mov_b64_e32 v[12:13], v[76:77]
	v_mov_b64_e32 v[14:15], v[78:79]
	v_mov_b64_e32 v[16:17], v[80:81]
	v_mov_b64_e32 v[18:19], v[82:83]
	v_mov_b64_e32 v[20:21], v[84:85]
	v_mov_b64_e32 v[22:23], v[86:87]
	v_mov_b64_e32 v[24:25], v[88:89]
	v_mov_b64_e32 v[26:27], v[90:91]
	v_mov_b64_e32 v[30:31], v[94:95]
	s_waitcnt vmcnt(0)
	v_mov_b32_e32 v29, v34
	v_mov_b64_e32 v[32:33], v[96:97]
	s_or_b64 exec, exec, s[0:1]
	s_and_saveexec_b64 s[0:1], vcc
	s_xor_b64 s[0:1], exec, s[0:1]
	s_cbranch_execnz .LBB0_106

; __device__ __forceinline__ void tr_load(const float* W, int N, int mat, int item, int lane, int nblk, float (&x)[32]) {
;     const int kb = item / nblk, nb = item % nblk, k0 = 64 * kb, n0 = 32 * nb;
;     const int sc = src_col(mat, n0 + (lane & 31));
; #pragma unroll
;     for (int i = 0; i < 32; ++i) { const int kk = 2 * i + (lane >> 5); x[i] = sc >= 0 ? W[(size_t)(k0 + kk) * N + sc] : 0.f; }
; }
.LBB0_225:
	v_or_b32_e32 v30, 56, v1
	s_mov_b32 s8, 0xd600
	v_mad_i64_i32 v[30:31], s[6:7], v30, s8, v[100:101]
	s_waitcnt vmcnt(1)
	v_or_b32_e32 v32, 58, v1
	s_waitcnt vmcnt(0)
	v_mad_i64_i32 v[32:33], s[6:7], v32, s8, v[100:101]
	global_load_dword v30, v[30:31], off nt
	s_nop 0
	global_load_dword v31, v[32:33], off nt
	s_or_b64 exec, exec, s[0:1]
	s_and_saveexec_b64 s[0:1], vcc
	s_xor_b64 s[0:1], exec, s[0:1]
	s_cbranch_execnz .LBB0_108
	s_branch .LBB0_109
